# knorm prefetch loop: trip-dependent exact vmcnt (20 in steady trips, 12 on first/last) instead of the conservative 12, so waits no longer include older stores; bit-identical; on top of v55
# baseline (speedup 1.0000x reference)
; __device__ __forceinline__ float bf2f(unsigned short u) { return __uint_as_float((unsigned)u << 16); }
; __device__ __forceinline__ unsigned f2bf(float f) { unsigned u = __float_as_uint(f); return (u + 0x7fffu + ((u >> 16) & 1u)) >> 16; }
; __device__ __forceinline__ void knorm_item(const KArgs& a, int l, int item, int wave, int lane) {
;     ...
;     for (int r0 = 0; r0 < 128; r0 += 16) {
;         float v[16];
; #pragma unroll
;         for (int i = 0; i < 16; ++i) { const int task = item * 1024 + wave * 128 + r0 + i, row = task >> 2, which = (task >> 1) & 1, g = task & 1;
;             v[i] = bf2f(Z[(size_t)row * ZW + (which ? ZC_KW : ZC_KS) + g * 64 + lane]); }
; #pragma unroll
;         for (int i = 0; i < 16; ++i) { const int task = item * 1024 + wave * 128 + r0 + i, row = task >> 2, which = (task >> 1) & 1, g = task & 1;
;             const float rstd = rsqrtf(wave_sum(v[i] * v[i]) * (1.f / 64.f) + EPS);
;             bf16_t* dst = (bf16_t*)(a.ws + (which ? WS_KWN : WS_KSN));
;             dst[(size_t)row * 128 + g * 64 + lane] = (bf16_t)f2bf(v[i] * rstd * kg); }
.LBB0_237:
	s_add_i32 s0, s24, s57
	s_add_i32 s0, s0, 0xfff80020
	s_ashr_i32 s4, s0, 2
	s_ashr_i32 s5, s4, 31
	s_mul_i32 s0, s4, 0x1a00
	s_mul_hi_i32 s1, s4, 0x1a00
	s_add_u32 s0, s92, s0
	s_addc_u32 s1, s93, s1
	v_lshl_add_u64 v[0:1], s[0:1], 0, v[196:197]
	global_load_dword v21, v[0:1], off offset:1024
	global_load_dword v22, v[0:1], off offset:1536
	s_add_u32 s0, s0, 0x1a00
	s_addc_u32 s1, s1, 0
	v_lshl_add_u64 v[2:3], s[0:1], 0, v[196:197]
	global_load_dword v19, v[2:3], off offset:1024
	global_load_dword v20, v[2:3], off offset:1536
	s_add_u32 s0, s0, 0x1a00
	s_addc_u32 s1, s1, 0
	v_lshl_add_u64 v[0:1], s[0:1], 0, v[196:197]
	global_load_dword v17, v[0:1], off offset:1024
	global_load_dword v18, v[0:1], off offset:1536
	s_add_u32 s0, s0, 0x1a00
	s_addc_u32 s1, s1, 0
	v_lshl_add_u64 v[2:3], s[0:1], 0, v[196:197]
	global_load_dword v15, v[2:3], off offset:1024
	global_load_dword v16, v[2:3], off offset:1536
	s_add_i32 s0, s24, s57
	s_add_i32 s0, s0, 0xfff80010
	s_ashr_i32 s4, s0, 2
	s_ashr_i32 s5, s4, 31
	s_lshl_b64 s[30:31], s[4:5], 8
	v_lshl_add_u64 v[200:201], v[190:191], 0, s[30:31]
	v_lshl_add_u64 v[202:203], v[192:193], 0, s[30:31]
	s_cmp_eq_i32 s57, -16
	s_cbranch_scc1 .Lkn5_s_237_0_0
	s_waitcnt vmcnt(20)
	s_branch .Lkn5_e_237_0_0
.Lkn5_s_237_0_0:
	s_waitcnt vmcnt(12)
.Lkn5_e_237_0_0:
	v_lshlrev_b32_e32 v220, 16, v4
	v_and_b32_e32 v221, 0xffff0000, v4
	v_lshlrev_b32_e32 v228, 16, v6
	v_and_b32_e32 v229, 0xffff0000, v6
	v_lshlrev_b32_e32 v236, 16, v27
	v_and_b32_e32 v237, 0xffff0000, v27
	v_lshlrev_b32_e32 v244, 16, v28
	v_and_b32_e32 v245, 0xffff0000, v28
	v_mul_f32_e32 v224, v220, v220
	v_mul_f32_e32 v225, v221, v221
	v_mul_f32_e32 v232, v228, v228
	v_mul_f32_e32 v233, v229, v229
	v_mul_f32_e32 v240, v236, v236
	v_mul_f32_e32 v241, v237, v237
	v_mul_f32_e32 v248, v244, v244
	v_mul_f32_e32 v249, v245, v245
	v_fma_f32 v222, v220, v220, v225
	v_fma_f32 v223, v221, v221, v224
	v_fma_f32 v230, v228, v228, v233
	v_fma_f32 v231, v229, v229, v232
	v_fma_f32 v238, v236, v236, v241
	v_fma_f32 v239, v237, v237, v240
	v_fma_f32 v246, v244, v244, v249
	v_fma_f32 v247, v245, v245, v248
	v_add_f32_dpp v222, v222, v222 quad_perm:[1,0,3,2] row_mask:0xf bank_mask:0xf
	v_add_f32_dpp v223, v223, v223 quad_perm:[1,0,3,2] row_mask:0xf bank_mask:0xf
	v_add_f32_dpp v230, v230, v230 quad_perm:[1,0,3,2] row_mask:0xf bank_mask:0xf
	v_add_f32_dpp v231, v231, v231 quad_perm:[1,0,3,2] row_mask:0xf bank_mask:0xf
	v_add_f32_dpp v238, v238, v238 quad_perm:[1,0,3,2] row_mask:0xf bank_mask:0xf
	v_add_f32_dpp v239, v239, v239 quad_perm:[1,0,3,2] row_mask:0xf bank_mask:0xf
	v_add_f32_dpp v246, v246, v246 quad_perm:[1,0,3,2] row_mask:0xf bank_mask:0xf
	v_add_f32_dpp v247, v247, v247 quad_perm:[1,0,3,2] row_mask:0xf bank_mask:0xf
	v_add_f32_dpp v222, v222, v222 quad_perm:[2,3,0,1] row_mask:0xf bank_mask:0xf
	v_add_f32_dpp v223, v223, v223 quad_perm:[2,3,0,1] row_mask:0xf bank_mask:0xf
	v_add_f32_dpp v230, v230, v230 quad_perm:[2,3,0,1] row_mask:0xf bank_mask:0xf
	v_add_f32_dpp v231, v231, v231 quad_perm:[2,3,0,1] row_mask:0xf bank_mask:0xf
	v_add_f32_dpp v238, v238, v238 quad_perm:[2,3,0,1] row_mask:0xf bank_mask:0xf
	v_add_f32_dpp v239, v239, v239 quad_perm:[2,3,0,1] row_mask:0xf bank_mask:0xf
	v_add_f32_dpp v246, v246, v246 quad_perm:[2,3,0,1] row_mask:0xf bank_mask:0xf
	v_add_f32_dpp v247, v247, v247 quad_perm:[2,3,0,1] row_mask:0xf bank_mask:0xf
	ds_bpermute_b32 v224, v11, v222
	ds_bpermute_b32 v225, v11, v223
	ds_bpermute_b32 v232, v11, v230
	ds_bpermute_b32 v233, v11, v231
	ds_bpermute_b32 v240, v11, v238
	ds_bpermute_b32 v241, v11, v239
	ds_bpermute_b32 v248, v11, v246
	ds_bpermute_b32 v249, v11, v247
	s_waitcnt lgkmcnt(0)
	v_add_f32_e32 v222, v222, v224
	v_add_f32_e32 v223, v223, v225
	v_add_f32_e32 v230, v230, v232
	v_add_f32_e32 v231, v231, v233
	v_add_f32_e32 v238, v238, v240
	v_add_f32_e32 v239, v239, v241
	v_add_f32_e32 v246, v246, v248
	v_add_f32_e32 v247, v247, v249
	v_add_f32_dpp v222, v222, v222 row_ror:8 row_mask:0xf bank_mask:0xf
	v_add_f32_dpp v223, v223, v223 row_ror:8 row_mask:0xf bank_mask:0xf
	v_add_f32_dpp v230, v230, v230 row_ror:8 row_mask:0xf bank_mask:0xf
	v_add_f32_dpp v231, v231, v231 row_ror:8 row_mask:0xf bank_mask:0xf
	v_add_f32_dpp v238, v238, v238 row_ror:8 row_mask:0xf bank_mask:0xf
	v_add_f32_dpp v239, v239, v239 row_ror:8 row_mask:0xf bank_mask:0xf
	v_add_f32_dpp v246, v246, v246 row_ror:8 row_mask:0xf bank_mask:0xf
	v_add_f32_dpp v247, v247, v247 row_ror:8 row_mask:0xf bank_mask:0xf
	ds_bpermute_b32 v224, v13, v222
	ds_bpermute_b32 v225, v13, v223
	ds_bpermute_b32 v232, v13, v230
	ds_bpermute_b32 v233, v13, v231
	ds_bpermute_b32 v240, v13, v238
	ds_bpermute_b32 v241, v13, v239
	ds_bpermute_b32 v248, v13, v246
	ds_bpermute_b32 v249, v13, v247
	s_waitcnt lgkmcnt(0)
; __device__ __forceinline__ float bf2f(unsigned short u) { return __uint_as_float((unsigned)u << 16); }
; __device__ __forceinline__ unsigned f2bf(float f) { unsigned u = __float_as_uint(f); return (u + 0x7fffu + ((u >> 16) & 1u)) >> 16; }
; __device__ __forceinline__ void knorm_item(const KArgs& a, int l, int item, int wave, int lane) {
;     ...
;     for (int r0 = 0; r0 < 128; r0 += 16) {
;         float v[16];
; #pragma unroll
;         for (int i = 0; i < 16; ++i) { const int task = item * 1024 + wave * 128 + r0 + i, row = task >> 2, which = (task >> 1) & 1, g = task & 1;
;             v[i] = bf2f(Z[(size_t)row * ZW + (which ? ZC_KW : ZC_KS) + g * 64 + lane]); }
; #pragma unroll
;         for (int i = 0; i < 16; ++i) { const int task = item * 1024 + wave * 128 + r0 + i, row = task >> 2, which = (task >> 1) & 1, g = task & 1;
;             const float rstd = rsqrtf(wave_sum(v[i] * v[i]) * (1.f / 64.f) + EPS);
;             bf16_t* dst = (bf16_t*)(a.ws + (which ? WS_KWN : WS_KSN));
;             dst[(size_t)row * 128 + g * 64 + lane] = (bf16_t)f2bf(v[i] * rstd * kg); }
	v_add_f32_e32 v222, v222, v224
	v_add_f32_e32 v223, v223, v225
	v_add_f32_e32 v230, v230, v232
	v_add_f32_e32 v231, v231, v233
	v_add_f32_e32 v238, v238, v240
	v_add_f32_e32 v239, v239, v241
	v_add_f32_e32 v246, v246, v248
	v_add_f32_e32 v247, v247, v249
	v_fma_f32 v222, v222, s22, v195
	v_fma_f32 v223, v223, s22, v195
	v_fma_f32 v230, v230, s22, v195
	v_fma_f32 v231, v231, s22, v195
	v_fma_f32 v238, v238, s22, v195
	v_fma_f32 v239, v239, s22, v195
	v_fma_f32 v246, v246, s22, v195
	v_fma_f32 v247, v247, s22, v195
	v_mul_f32_e32 v226, 0x4b800000, v222
	    v_mul_f32_e32 v227, 0x4b800000, v223
	    v_cmp_gt_f32_e64 s[4:5], s48, v222
	    v_cmp_gt_f32_e32 vcc, s48, v223
	    s_nop 1
	    v_cndmask_b32_e64 v222, v222, v226, s[4:5]
	    v_cndmask_b32_e32 v223, v223, v227, vcc
	    v_rsq_f32_e32 v222, v222
	    v_rsq_f32_e32 v223, v223
	    s_nop 0
	    v_mul_f32_e32 v226, 0x45800000, v222
	    v_mul_f32_e32 v227, 0x45800000, v223
	    v_cndmask_b32_e64 v222, v222, v226, s[4:5]
	    v_cndmask_b32_e32 v223, v223, v227, vcc
	    v_mul_f32_e32 v220, v222, v220
	    v_mul_f32_e32 v221, v223, v221
	    v_mul_f32_e32 v220, v184, v220
	    v_mul_f32_e32 v221, v185, v221
	    v_bfe_u32 v226, v220, 16, 1
	    v_bfe_u32 v227, v221, 16, 1
	    v_add3_u32 v220, v220, v226, s49
	    v_add3_u32 v221, v221, v227, s49
	    v_perm_b32 v4, v221, v220, v194
	    global_store_dword v[200:201], v4, off
	v_mul_f32_e32 v234, 0x4b800000, v230
	    v_mul_f32_e32 v235, 0x4b800000, v231
	    v_cmp_gt_f32_e64 s[4:5], s48, v230
	    v_cmp_gt_f32_e32 vcc, s48, v231
	    s_nop 1
	    v_cndmask_b32_e64 v230, v230, v234, s[4:5]
	    v_cndmask_b32_e32 v231, v231, v235, vcc
	    v_rsq_f32_e32 v230, v230
	    v_rsq_f32_e32 v231, v231
	    s_nop 0
	    v_mul_f32_e32 v234, 0x45800000, v230
	    v_mul_f32_e32 v235, 0x45800000, v231
	    v_cndmask_b32_e64 v230, v230, v234, s[4:5]
	    v_cndmask_b32_e32 v231, v231, v235, vcc
	    v_mul_f32_e32 v228, v230, v228
	    v_mul_f32_e32 v229, v231, v229
	    v_mul_f32_e32 v228, v184, v228
	    v_mul_f32_e32 v229, v185, v229
	    v_bfe_u32 v234, v228, 16, 1
	    v_bfe_u32 v235, v229, 16, 1
	    v_add3_u32 v228, v228, v234, s49
	    v_add3_u32 v229, v229, v235, s49
	    v_perm_b32 v6, v229, v228, v194
	    global_store_dword v[202:203], v6, off
	v_mul_f32_e32 v242, 0x4b800000, v238
	    v_mul_f32_e32 v243, 0x4b800000, v239
	    v_cmp_gt_f32_e64 s[4:5], s48, v238
	    v_cmp_gt_f32_e32 vcc, s48, v239
	    s_nop 1
	    v_cndmask_b32_e64 v238, v238, v242, s[4:5]
	    v_cndmask_b32_e32 v239, v239, v243, vcc
	    v_rsq_f32_e32 v238, v238
	    v_rsq_f32_e32 v239, v239
	    s_nop 0
	    v_mul_f32_e32 v242, 0x45800000, v238
	    v_mul_f32_e32 v243, 0x45800000, v239
	    v_cndmask_b32_e64 v238, v238, v242, s[4:5]
	    v_cndmask_b32_e32 v239, v239, v243, vcc
	    v_mul_f32_e32 v236, v238, v236
	    v_mul_f32_e32 v237, v239, v237
	    v_mul_f32_e32 v236, v184, v236
	    v_mul_f32_e32 v237, v185, v237
	    v_bfe_u32 v242, v236, 16, 1
	    v_bfe_u32 v243, v237, 16, 1
	    v_add3_u32 v236, v236, v242, s49
	    v_add3_u32 v237, v237, v243, s49
	    v_perm_b32 v27, v237, v236, v194
	    global_store_dword v[200:201], v27, off offset:256
	v_mul_f32_e32 v250, 0x4b800000, v246
	    v_mul_f32_e32 v251, 0x4b800000, v247
	    v_cmp_gt_f32_e64 s[4:5], s48, v246
	    v_cmp_gt_f32_e32 vcc, s48, v247
	    s_nop 1
	    v_cndmask_b32_e64 v246, v246, v250, s[4:5]
	    v_cndmask_b32_e32 v247, v247, v251, vcc
	    v_rsq_f32_e32 v246, v246
	    v_rsq_f32_e32 v247, v247
	    s_nop 0
	    v_mul_f32_e32 v250, 0x45800000, v246
	    v_mul_f32_e32 v251, 0x45800000, v247
	    v_cndmask_b32_e64 v246, v246, v250, s[4:5]
	    v_cndmask_b32_e32 v247, v247, v251, vcc
	    v_mul_f32_e32 v244, v246, v244
	    v_mul_f32_e32 v245, v247, v245
	    v_mul_f32_e32 v244, v184, v244
	    v_mul_f32_e32 v245, v185, v245
	    v_bfe_u32 v250, v244, 16, 1
	    v_bfe_u32 v251, v245, 16, 1
	    v_add3_u32 v244, v244, v250, s49
	    v_add3_u32 v245, v245, v251, s49
	    v_perm_b32 v28, v245, v244, v194
	    global_store_dword v[202:203], v28, off offset:256
	s_cmp_eq_i32 s57, -16
	s_cbranch_scc1 .Lkn5_s_237_0_1
	s_waitcnt vmcnt(20)
	s_branch .Lkn5_e_237_0_1

; __device__ __forceinline__ float bf2f(unsigned short u) { return __uint_as_float((unsigned)u << 16); }
; __device__ __forceinline__ unsigned f2bf(float f) { unsigned u = __float_as_uint(f); return (u + 0x7fffu + ((u >> 16) & 1u)) >> 16; }
; __device__ __forceinline__ void knorm_item(const KArgs& a, int l, int item, int wave, int lane) {
;     ...
;     for (int r0 = 0; r0 < 128; r0 += 16) {
;         float v[16];
; #pragma unroll
;         for (int i = 0; i < 16; ++i) { const int task = item * 1024 + wave * 128 + r0 + i, row = task >> 2, which = (task >> 1) & 1, g = task & 1;
;             v[i] = bf2f(Z[(size_t)row * ZW + (which ? ZC_KW : ZC_KS) + g * 64 + lane]); }
; #pragma unroll
;         for (int i = 0; i < 16; ++i) { const int task = item * 1024 + wave * 128 + r0 + i, row = task >> 2, which = (task >> 1) & 1, g = task & 1;
;             const float rstd = rsqrtf(wave_sum(v[i] * v[i]) * (1.f / 64.f) + EPS);
;             bf16_t* dst = (bf16_t*)(a.ws + (which ? WS_KWN : WS_KSN));
;             dst[(size_t)row * 128 + g * 64 + lane] = (bf16_t)f2bf(v[i] * rstd * kg); }
.Lkn5_e_237_0_1:
	v_lshlrev_b32_e32 v220, 16, v25
	v_and_b32_e32 v221, 0xffff0000, v25
	v_lshlrev_b32_e32 v228, 16, v26
	v_and_b32_e32 v229, 0xffff0000, v26
	v_lshlrev_b32_e32 v236, 16, v23
	v_and_b32_e32 v237, 0xffff0000, v23
	v_lshlrev_b32_e32 v244, 16, v24
	v_and_b32_e32 v245, 0xffff0000, v24
	v_mul_f32_e32 v224, v220, v220
	v_mul_f32_e32 v225, v221, v221
	v_mul_f32_e32 v232, v228, v228
	v_mul_f32_e32 v233, v229, v229
	v_mul_f32_e32 v240, v236, v236
	v_mul_f32_e32 v241, v237, v237
	v_mul_f32_e32 v248, v244, v244
	v_mul_f32_e32 v249, v245, v245
	v_fma_f32 v222, v220, v220, v225
	v_fma_f32 v223, v221, v221, v224
	v_fma_f32 v230, v228, v228, v233
	v_fma_f32 v231, v229, v229, v232
	v_fma_f32 v238, v236, v236, v241
	v_fma_f32 v239, v237, v237, v240
	v_fma_f32 v246, v244, v244, v249
	v_fma_f32 v247, v245, v245, v248
	v_add_f32_dpp v222, v222, v222 quad_perm:[1,0,3,2] row_mask:0xf bank_mask:0xf
	v_add_f32_dpp v223, v223, v223 quad_perm:[1,0,3,2] row_mask:0xf bank_mask:0xf
	v_add_f32_dpp v230, v230, v230 quad_perm:[1,0,3,2] row_mask:0xf bank_mask:0xf
	v_add_f32_dpp v231, v231, v231 quad_perm:[1,0,3,2] row_mask:0xf bank_mask:0xf
	v_add_f32_dpp v238, v238, v238 quad_perm:[1,0,3,2] row_mask:0xf bank_mask:0xf
	v_add_f32_dpp v239, v239, v239 quad_perm:[1,0,3,2] row_mask:0xf bank_mask:0xf
	v_add_f32_dpp v246, v246, v246 quad_perm:[1,0,3,2] row_mask:0xf bank_mask:0xf
	v_add_f32_dpp v247, v247, v247 quad_perm:[1,0,3,2] row_mask:0xf bank_mask:0xf
	v_add_f32_dpp v222, v222, v222 quad_perm:[2,3,0,1] row_mask:0xf bank_mask:0xf
	v_add_f32_dpp v223, v223, v223 quad_perm:[2,3,0,1] row_mask:0xf bank_mask:0xf
	v_add_f32_dpp v230, v230, v230 quad_perm:[2,3,0,1] row_mask:0xf bank_mask:0xf
	v_add_f32_dpp v231, v231, v231 quad_perm:[2,3,0,1] row_mask:0xf bank_mask:0xf
	v_add_f32_dpp v238, v238, v238 quad_perm:[2,3,0,1] row_mask:0xf bank_mask:0xf
	v_add_f32_dpp v239, v239, v239 quad_perm:[2,3,0,1] row_mask:0xf bank_mask:0xf
	v_add_f32_dpp v246, v246, v246 quad_perm:[2,3,0,1] row_mask:0xf bank_mask:0xf
	v_add_f32_dpp v247, v247, v247 quad_perm:[2,3,0,1] row_mask:0xf bank_mask:0xf
	ds_bpermute_b32 v224, v11, v222
	ds_bpermute_b32 v225, v11, v223
	ds_bpermute_b32 v232, v11, v230
	ds_bpermute_b32 v233, v11, v231
	ds_bpermute_b32 v240, v11, v238
	ds_bpermute_b32 v241, v11, v239
	ds_bpermute_b32 v248, v11, v246
	ds_bpermute_b32 v249, v11, v247
	s_waitcnt lgkmcnt(0)
	v_add_f32_e32 v222, v222, v224
	v_add_f32_e32 v223, v223, v225
	v_add_f32_e32 v230, v230, v232
	v_add_f32_e32 v231, v231, v233
	v_add_f32_e32 v238, v238, v240
	v_add_f32_e32 v239, v239, v241
	v_add_f32_e32 v246, v246, v248
	v_add_f32_e32 v247, v247, v249
	v_add_f32_dpp v222, v222, v222 row_ror:8 row_mask:0xf bank_mask:0xf
	v_add_f32_dpp v223, v223, v223 row_ror:8 row_mask:0xf bank_mask:0xf
	v_add_f32_dpp v230, v230, v230 row_ror:8 row_mask:0xf bank_mask:0xf
	v_add_f32_dpp v231, v231, v231 row_ror:8 row_mask:0xf bank_mask:0xf
	v_add_f32_dpp v238, v238, v238 row_ror:8 row_mask:0xf bank_mask:0xf
	v_add_f32_dpp v239, v239, v239 row_ror:8 row_mask:0xf bank_mask:0xf
	v_add_f32_dpp v246, v246, v246 row_ror:8 row_mask:0xf bank_mask:0xf
	v_add_f32_dpp v247, v247, v247 row_ror:8 row_mask:0xf bank_mask:0xf
	ds_bpermute_b32 v224, v13, v222
	ds_bpermute_b32 v225, v13, v223
	ds_bpermute_b32 v232, v13, v230
	ds_bpermute_b32 v233, v13, v231
	ds_bpermute_b32 v240, v13, v238
	ds_bpermute_b32 v241, v13, v239
	ds_bpermute_b32 v248, v13, v246
	ds_bpermute_b32 v249, v13, v247
	s_waitcnt lgkmcnt(0)
; __device__ __forceinline__ float bf2f(unsigned short u) { return __uint_as_float((unsigned)u << 16); }
; __device__ __forceinline__ unsigned f2bf(float f) { unsigned u = __float_as_uint(f); return (u + 0x7fffu + ((u >> 16) & 1u)) >> 16; }
; __device__ __forceinline__ void knorm_item(const KArgs& a, int l, int item, int wave, int lane) {
;     ...
;     for (int r0 = 0; r0 < 128; r0 += 16) {
;         float v[16];
; #pragma unroll
;         for (int i = 0; i < 16; ++i) { const int task = item * 1024 + wave * 128 + r0 + i, row = task >> 2, which = (task >> 1) & 1, g = task & 1;
;             v[i] = bf2f(Z[(size_t)row * ZW + (which ? ZC_KW : ZC_KS) + g * 64 + lane]); }
; #pragma unroll
;         for (int i = 0; i < 16; ++i) { const int task = item * 1024 + wave * 128 + r0 + i, row = task >> 2, which = (task >> 1) & 1, g = task & 1;
;             const float rstd = rsqrtf(wave_sum(v[i] * v[i]) * (1.f / 64.f) + EPS);
;             bf16_t* dst = (bf16_t*)(a.ws + (which ? WS_KWN : WS_KSN));
;             dst[(size_t)row * 128 + g * 64 + lane] = (bf16_t)f2bf(v[i] * rstd * kg); }
	v_add_f32_e32 v222, v222, v224
	v_add_f32_e32 v223, v223, v225
	v_add_f32_e32 v230, v230, v232
	v_add_f32_e32 v231, v231, v233
	v_add_f32_e32 v238, v238, v240
	v_add_f32_e32 v239, v239, v241
	v_add_f32_e32 v246, v246, v248
	v_add_f32_e32 v247, v247, v249
	v_fma_f32 v222, v222, s22, v195
	v_fma_f32 v223, v223, s22, v195
	v_fma_f32 v230, v230, s22, v195
	v_fma_f32 v231, v231, s22, v195
	v_fma_f32 v238, v238, s22, v195
	v_fma_f32 v239, v239, s22, v195
	v_fma_f32 v246, v246, s22, v195
	v_fma_f32 v247, v247, s22, v195
	v_mul_f32_e32 v226, 0x4b800000, v222
	    v_mul_f32_e32 v227, 0x4b800000, v223
	    v_cmp_gt_f32_e64 s[4:5], s48, v222
	    v_cmp_gt_f32_e32 vcc, s48, v223
	    s_nop 1
	    v_cndmask_b32_e64 v222, v222, v226, s[4:5]
	    v_cndmask_b32_e32 v223, v223, v227, vcc
	    v_rsq_f32_e32 v222, v222
	    v_rsq_f32_e32 v223, v223
	    s_nop 0
	    v_mul_f32_e32 v226, 0x45800000, v222
	    v_mul_f32_e32 v227, 0x45800000, v223
	    v_cndmask_b32_e64 v222, v222, v226, s[4:5]
	    v_cndmask_b32_e32 v223, v223, v227, vcc
	    v_mul_f32_e32 v220, v222, v220
	    v_mul_f32_e32 v221, v223, v221
	    v_mul_f32_e32 v220, v184, v220
	    v_mul_f32_e32 v221, v185, v221
	    v_bfe_u32 v226, v220, 16, 1
	    v_bfe_u32 v227, v221, 16, 1
	    v_add3_u32 v220, v220, v226, s49
	    v_add3_u32 v221, v221, v227, s49
	    v_perm_b32 v25, v221, v220, v194
	    global_store_dword v[200:201], v25, off offset:512
	v_mul_f32_e32 v234, 0x4b800000, v230
	    v_mul_f32_e32 v235, 0x4b800000, v231
	    v_cmp_gt_f32_e64 s[4:5], s48, v230
	    v_cmp_gt_f32_e32 vcc, s48, v231
	    s_nop 1
	    v_cndmask_b32_e64 v230, v230, v234, s[4:5]
	    v_cndmask_b32_e32 v231, v231, v235, vcc
	    v_rsq_f32_e32 v230, v230
	    v_rsq_f32_e32 v231, v231
	    s_nop 0
	    v_mul_f32_e32 v234, 0x45800000, v230
	    v_mul_f32_e32 v235, 0x45800000, v231
	    v_cndmask_b32_e64 v230, v230, v234, s[4:5]
	    v_cndmask_b32_e32 v231, v231, v235, vcc
	    v_mul_f32_e32 v228, v230, v228
	    v_mul_f32_e32 v229, v231, v229
	    v_mul_f32_e32 v228, v184, v228
	    v_mul_f32_e32 v229, v185, v229
	    v_bfe_u32 v234, v228, 16, 1
	    v_bfe_u32 v235, v229, 16, 1
	    v_add3_u32 v228, v228, v234, s49
	    v_add3_u32 v229, v229, v235, s49
	    v_perm_b32 v26, v229, v228, v194
	    global_store_dword v[202:203], v26, off offset:512
	v_mul_f32_e32 v242, 0x4b800000, v238
	    v_mul_f32_e32 v243, 0x4b800000, v239
	    v_cmp_gt_f32_e64 s[4:5], s48, v238
	    v_cmp_gt_f32_e32 vcc, s48, v239
	    s_nop 1
	    v_cndmask_b32_e64 v238, v238, v242, s[4:5]
	    v_cndmask_b32_e32 v239, v239, v243, vcc
	    v_rsq_f32_e32 v238, v238
	    v_rsq_f32_e32 v239, v239
	    s_nop 0
	    v_mul_f32_e32 v242, 0x45800000, v238
	    v_mul_f32_e32 v243, 0x45800000, v239
	    v_cndmask_b32_e64 v238, v238, v242, s[4:5]
	    v_cndmask_b32_e32 v239, v239, v243, vcc
	    v_mul_f32_e32 v236, v238, v236
	    v_mul_f32_e32 v237, v239, v237
	    v_mul_f32_e32 v236, v184, v236
	    v_mul_f32_e32 v237, v185, v237
	    v_bfe_u32 v242, v236, 16, 1
	    v_bfe_u32 v243, v237, 16, 1
	    v_add3_u32 v236, v236, v242, s49
	    v_add3_u32 v237, v237, v243, s49
	    v_perm_b32 v23, v237, v236, v194
	    global_store_dword v[200:201], v23, off offset:768
	v_mul_f32_e32 v250, 0x4b800000, v246
	    v_mul_f32_e32 v251, 0x4b800000, v247
	    v_cmp_gt_f32_e64 s[4:5], s48, v246
	    v_cmp_gt_f32_e32 vcc, s48, v247
	    s_nop 1
	    v_cndmask_b32_e64 v246, v246, v250, s[4:5]
	    v_cndmask_b32_e32 v247, v247, v251, vcc
	    v_rsq_f32_e32 v246, v246
	    v_rsq_f32_e32 v247, v247
	    s_nop 0
	    v_mul_f32_e32 v250, 0x45800000, v246
	    v_mul_f32_e32 v251, 0x45800000, v247
	    v_cndmask_b32_e64 v246, v246, v250, s[4:5]
	    v_cndmask_b32_e32 v247, v247, v251, vcc
	    v_mul_f32_e32 v244, v246, v244
	    v_mul_f32_e32 v245, v247, v245
	    v_mul_f32_e32 v244, v184, v244
	    v_mul_f32_e32 v245, v185, v245
	    v_bfe_u32 v250, v244, 16, 1
	    v_bfe_u32 v251, v245, 16, 1
	    v_add3_u32 v244, v244, v250, s49
	    v_add3_u32 v245, v245, v251, s49
	    v_perm_b32 v24, v245, v244, v194
	    global_store_dword v[202:203], v24, off offset:768
	s_cmpk_gt_i32 s57, 64
	s_cbranch_scc1 .Lkn5_skip_237
	s_add_i32 s0, s24, s57
	s_add_i32 s0, s0, 0xfff80030
	s_ashr_i32 s4, s0, 2
	s_ashr_i32 s5, s4, 31
	s_mul_i32 s0, s4, 0x1a00
	s_mul_hi_i32 s1, s4, 0x1a00
	s_add_u32 s0, s92, s0
	s_addc_u32 s1, s93, s1
	v_lshl_add_u64 v[0:1], s[0:1], 0, v[196:197]
	global_load_dword v4, v[0:1], off offset:1024
	global_load_dword v6, v[0:1], off offset:1536
	s_add_u32 s0, s0, 0x1a00
	s_addc_u32 s1, s1, 0
	v_lshl_add_u64 v[2:3], s[0:1], 0, v[196:197]
	global_load_dword v27, v[2:3], off offset:1024
	global_load_dword v28, v[2:3], off offset:1536
	s_add_u32 s0, s0, 0x1a00
	s_addc_u32 s1, s1, 0
	v_lshl_add_u64 v[0:1], s[0:1], 0, v[196:197]
	global_load_dword v25, v[0:1], off offset:1024
	global_load_dword v26, v[0:1], off offset:1536
	s_add_u32 s0, s0, 0x1a00
	s_addc_u32 s1, s1, 0
	v_lshl_add_u64 v[2:3], s[0:1], 0, v[196:197]
	global_load_dword v23, v[2:3], off offset:1024
	global_load_dword v24, v[2:3], off offset:1536
.Lkn5_skip_237:
	s_add_i32 s0, s24, s57
	s_add_i32 s0, s0, 0xfff80020
	s_ashr_i32 s4, s0, 2
	s_ashr_i32 s5, s4, 31
	s_lshl_b64 s[30:31], s[4:5], 8
	v_lshl_add_u64 v[200:201], v[190:191], 0, s[30:31]
	v_lshl_add_u64 v[202:203], v[192:193], 0, s[30:31]
	s_cmpk_eq_i32 s57, 0x50
	s_cbranch_scc1 .Lkn5_s_237_1_0
	s_waitcnt vmcnt(20)
	s_branch .Lkn5_e_237_1_0

; __device__ __forceinline__ float bf2f(unsigned short u) { return __uint_as_float((unsigned)u << 16); }
; __device__ __forceinline__ unsigned f2bf(float f) { unsigned u = __float_as_uint(f); return (u + 0x7fffu + ((u >> 16) & 1u)) >> 16; }
; __device__ __forceinline__ void knorm_item(const KArgs& a, int l, int item, int wave, int lane) {
;     ...
;     for (int r0 = 0; r0 < 128; r0 += 16) {
;         float v[16];
; #pragma unroll
;         for (int i = 0; i < 16; ++i) { const int task = item * 1024 + wave * 128 + r0 + i, row = task >> 2, which = (task >> 1) & 1, g = task & 1;
;             v[i] = bf2f(Z[(size_t)row * ZW + (which ? ZC_KW : ZC_KS) + g * 64 + lane]); }
; #pragma unroll
;         for (int i = 0; i < 16; ++i) { const int task = item * 1024 + wave * 128 + r0 + i, row = task >> 2, which = (task >> 1) & 1, g = task & 1;
;             const float rstd = rsqrtf(wave_sum(v[i] * v[i]) * (1.f / 64.f) + EPS);
;             bf16_t* dst = (bf16_t*)(a.ws + (which ? WS_KWN : WS_KSN));
;             dst[(size_t)row * 128 + g * 64 + lane] = (bf16_t)f2bf(v[i] * rstd * kg); }
.Lkn5_e_237_1_0:
	v_lshlrev_b32_e32 v220, 16, v21
	v_and_b32_e32 v221, 0xffff0000, v21
	v_lshlrev_b32_e32 v228, 16, v22
	v_and_b32_e32 v229, 0xffff0000, v22
	v_lshlrev_b32_e32 v236, 16, v19
	v_and_b32_e32 v237, 0xffff0000, v19
	v_lshlrev_b32_e32 v244, 16, v20
	v_and_b32_e32 v245, 0xffff0000, v20
	v_mul_f32_e32 v224, v220, v220
	v_mul_f32_e32 v225, v221, v221
	v_mul_f32_e32 v232, v228, v228
	v_mul_f32_e32 v233, v229, v229
	v_mul_f32_e32 v240, v236, v236
	v_mul_f32_e32 v241, v237, v237
	v_mul_f32_e32 v248, v244, v244
	v_mul_f32_e32 v249, v245, v245
	v_fma_f32 v222, v220, v220, v225
	v_fma_f32 v223, v221, v221, v224
	v_fma_f32 v230, v228, v228, v233
	v_fma_f32 v231, v229, v229, v232
	v_fma_f32 v238, v236, v236, v241
	v_fma_f32 v239, v237, v237, v240
	v_fma_f32 v246, v244, v244, v249
	v_fma_f32 v247, v245, v245, v248
	v_add_f32_dpp v222, v222, v222 quad_perm:[1,0,3,2] row_mask:0xf bank_mask:0xf
	v_add_f32_dpp v223, v223, v223 quad_perm:[1,0,3,2] row_mask:0xf bank_mask:0xf
	v_add_f32_dpp v230, v230, v230 quad_perm:[1,0,3,2] row_mask:0xf bank_mask:0xf
	v_add_f32_dpp v231, v231, v231 quad_perm:[1,0,3,2] row_mask:0xf bank_mask:0xf
	v_add_f32_dpp v238, v238, v238 quad_perm:[1,0,3,2] row_mask:0xf bank_mask:0xf
	v_add_f32_dpp v239, v239, v239 quad_perm:[1,0,3,2] row_mask:0xf bank_mask:0xf
	v_add_f32_dpp v246, v246, v246 quad_perm:[1,0,3,2] row_mask:0xf bank_mask:0xf
	v_add_f32_dpp v247, v247, v247 quad_perm:[1,0,3,2] row_mask:0xf bank_mask:0xf
	v_add_f32_dpp v222, v222, v222 quad_perm:[2,3,0,1] row_mask:0xf bank_mask:0xf
	v_add_f32_dpp v223, v223, v223 quad_perm:[2,3,0,1] row_mask:0xf bank_mask:0xf
	v_add_f32_dpp v230, v230, v230 quad_perm:[2,3,0,1] row_mask:0xf bank_mask:0xf
	v_add_f32_dpp v231, v231, v231 quad_perm:[2,3,0,1] row_mask:0xf bank_mask:0xf
	v_add_f32_dpp v238, v238, v238 quad_perm:[2,3,0,1] row_mask:0xf bank_mask:0xf
	v_add_f32_dpp v239, v239, v239 quad_perm:[2,3,0,1] row_mask:0xf bank_mask:0xf
	v_add_f32_dpp v246, v246, v246 quad_perm:[2,3,0,1] row_mask:0xf bank_mask:0xf
	v_add_f32_dpp v247, v247, v247 quad_perm:[2,3,0,1] row_mask:0xf bank_mask:0xf
	ds_bpermute_b32 v224, v11, v222
	ds_bpermute_b32 v225, v11, v223
	ds_bpermute_b32 v232, v11, v230
	ds_bpermute_b32 v233, v11, v231
	ds_bpermute_b32 v240, v11, v238
	ds_bpermute_b32 v241, v11, v239
	ds_bpermute_b32 v248, v11, v246
	ds_bpermute_b32 v249, v11, v247
	s_waitcnt lgkmcnt(0)
	v_add_f32_e32 v222, v222, v224
	v_add_f32_e32 v223, v223, v225
	v_add_f32_e32 v230, v230, v232
	v_add_f32_e32 v231, v231, v233
	v_add_f32_e32 v238, v238, v240
	v_add_f32_e32 v239, v239, v241
	v_add_f32_e32 v246, v246, v248
	v_add_f32_e32 v247, v247, v249
	v_add_f32_dpp v222, v222, v222 row_ror:8 row_mask:0xf bank_mask:0xf
	v_add_f32_dpp v223, v223, v223 row_ror:8 row_mask:0xf bank_mask:0xf
	v_add_f32_dpp v230, v230, v230 row_ror:8 row_mask:0xf bank_mask:0xf
	v_add_f32_dpp v231, v231, v231 row_ror:8 row_mask:0xf bank_mask:0xf
	v_add_f32_dpp v238, v238, v238 row_ror:8 row_mask:0xf bank_mask:0xf
	v_add_f32_dpp v239, v239, v239 row_ror:8 row_mask:0xf bank_mask:0xf
	v_add_f32_dpp v246, v246, v246 row_ror:8 row_mask:0xf bank_mask:0xf
	v_add_f32_dpp v247, v247, v247 row_ror:8 row_mask:0xf bank_mask:0xf
	ds_bpermute_b32 v224, v13, v222
	ds_bpermute_b32 v225, v13, v223
	ds_bpermute_b32 v232, v13, v230
	ds_bpermute_b32 v233, v13, v231
	ds_bpermute_b32 v240, v13, v238
	ds_bpermute_b32 v241, v13, v239
	ds_bpermute_b32 v248, v13, v246
	ds_bpermute_b32 v249, v13, v247
	s_waitcnt lgkmcnt(0)
; __device__ __forceinline__ float bf2f(unsigned short u) { return __uint_as_float((unsigned)u << 16); }
; __device__ __forceinline__ unsigned f2bf(float f) { unsigned u = __float_as_uint(f); return (u + 0x7fffu + ((u >> 16) & 1u)) >> 16; }
; __device__ __forceinline__ void knorm_item(const KArgs& a, int l, int item, int wave, int lane) {
;     ...
;     for (int r0 = 0; r0 < 128; r0 += 16) {
;         float v[16];
; #pragma unroll
;         for (int i = 0; i < 16; ++i) { const int task = item * 1024 + wave * 128 + r0 + i, row = task >> 2, which = (task >> 1) & 1, g = task & 1;
;             v[i] = bf2f(Z[(size_t)row * ZW + (which ? ZC_KW : ZC_KS) + g * 64 + lane]); }
; #pragma unroll
;         for (int i = 0; i < 16; ++i) { const int task = item * 1024 + wave * 128 + r0 + i, row = task >> 2, which = (task >> 1) & 1, g = task & 1;
;             const float rstd = rsqrtf(wave_sum(v[i] * v[i]) * (1.f / 64.f) + EPS);
;             bf16_t* dst = (bf16_t*)(a.ws + (which ? WS_KWN : WS_KSN));
;             dst[(size_t)row * 128 + g * 64 + lane] = (bf16_t)f2bf(v[i] * rstd * kg); }
	v_add_f32_e32 v222, v222, v224
	v_add_f32_e32 v223, v223, v225
	v_add_f32_e32 v230, v230, v232
	v_add_f32_e32 v231, v231, v233
	v_add_f32_e32 v238, v238, v240
	v_add_f32_e32 v239, v239, v241
	v_add_f32_e32 v246, v246, v248
	v_add_f32_e32 v247, v247, v249
	v_fma_f32 v222, v222, s22, v195
	v_fma_f32 v223, v223, s22, v195
	v_fma_f32 v230, v230, s22, v195
	v_fma_f32 v231, v231, s22, v195
	v_fma_f32 v238, v238, s22, v195
	v_fma_f32 v239, v239, s22, v195
	v_fma_f32 v246, v246, s22, v195
	v_fma_f32 v247, v247, s22, v195
	v_mul_f32_e32 v226, 0x4b800000, v222
	    v_mul_f32_e32 v227, 0x4b800000, v223
	    v_cmp_gt_f32_e64 s[4:5], s48, v222
	    v_cmp_gt_f32_e32 vcc, s48, v223
	    s_nop 1
	    v_cndmask_b32_e64 v222, v222, v226, s[4:5]
	    v_cndmask_b32_e32 v223, v223, v227, vcc
	    v_rsq_f32_e32 v222, v222
	    v_rsq_f32_e32 v223, v223
	    s_nop 0
	    v_mul_f32_e32 v226, 0x45800000, v222
	    v_mul_f32_e32 v227, 0x45800000, v223
	    v_cndmask_b32_e64 v222, v222, v226, s[4:5]
	    v_cndmask_b32_e32 v223, v223, v227, vcc
	    v_mul_f32_e32 v220, v222, v220
	    v_mul_f32_e32 v221, v223, v221
	    v_mul_f32_e32 v220, v184, v220
	    v_mul_f32_e32 v221, v185, v221
	    v_bfe_u32 v226, v220, 16, 1
	    v_bfe_u32 v227, v221, 16, 1
	    v_add3_u32 v220, v220, v226, s49
	    v_add3_u32 v221, v221, v227, s49
	    v_perm_b32 v21, v221, v220, v194
	    global_store_dword v[200:201], v21, off
	v_mul_f32_e32 v234, 0x4b800000, v230
	    v_mul_f32_e32 v235, 0x4b800000, v231
	    v_cmp_gt_f32_e64 s[4:5], s48, v230
	    v_cmp_gt_f32_e32 vcc, s48, v231
	    s_nop 1
	    v_cndmask_b32_e64 v230, v230, v234, s[4:5]
	    v_cndmask_b32_e32 v231, v231, v235, vcc
	    v_rsq_f32_e32 v230, v230
	    v_rsq_f32_e32 v231, v231
	    s_nop 0
	    v_mul_f32_e32 v234, 0x45800000, v230
	    v_mul_f32_e32 v235, 0x45800000, v231
	    v_cndmask_b32_e64 v230, v230, v234, s[4:5]
	    v_cndmask_b32_e32 v231, v231, v235, vcc
	    v_mul_f32_e32 v228, v230, v228
	    v_mul_f32_e32 v229, v231, v229
	    v_mul_f32_e32 v228, v184, v228
	    v_mul_f32_e32 v229, v185, v229
	    v_bfe_u32 v234, v228, 16, 1
	    v_bfe_u32 v235, v229, 16, 1
	    v_add3_u32 v228, v228, v234, s49
	    v_add3_u32 v229, v229, v235, s49
	    v_perm_b32 v22, v229, v228, v194
	    global_store_dword v[202:203], v22, off
	v_mul_f32_e32 v242, 0x4b800000, v238
	    v_mul_f32_e32 v243, 0x4b800000, v239
	    v_cmp_gt_f32_e64 s[4:5], s48, v238
	    v_cmp_gt_f32_e32 vcc, s48, v239
	    s_nop 1
	    v_cndmask_b32_e64 v238, v238, v242, s[4:5]
	    v_cndmask_b32_e32 v239, v239, v243, vcc
	    v_rsq_f32_e32 v238, v238
	    v_rsq_f32_e32 v239, v239
	    s_nop 0
	    v_mul_f32_e32 v242, 0x45800000, v238
	    v_mul_f32_e32 v243, 0x45800000, v239
	    v_cndmask_b32_e64 v238, v238, v242, s[4:5]
	    v_cndmask_b32_e32 v239, v239, v243, vcc
	    v_mul_f32_e32 v236, v238, v236
	    v_mul_f32_e32 v237, v239, v237
	    v_mul_f32_e32 v236, v184, v236
	    v_mul_f32_e32 v237, v185, v237
	    v_bfe_u32 v242, v236, 16, 1
	    v_bfe_u32 v243, v237, 16, 1
	    v_add3_u32 v236, v236, v242, s49
	    v_add3_u32 v237, v237, v243, s49
	    v_perm_b32 v19, v237, v236, v194
	    global_store_dword v[200:201], v19, off offset:256
	v_mul_f32_e32 v250, 0x4b800000, v246
	    v_mul_f32_e32 v251, 0x4b800000, v247
	    v_cmp_gt_f32_e64 s[4:5], s48, v246
	    v_cmp_gt_f32_e32 vcc, s48, v247
	    s_nop 1
	    v_cndmask_b32_e64 v246, v246, v250, s[4:5]
	    v_cndmask_b32_e32 v247, v247, v251, vcc
	    v_rsq_f32_e32 v246, v246
	    v_rsq_f32_e32 v247, v247
	    s_nop 0
	    v_mul_f32_e32 v250, 0x45800000, v246
	    v_mul_f32_e32 v251, 0x45800000, v247
	    v_cndmask_b32_e64 v246, v246, v250, s[4:5]
	    v_cndmask_b32_e32 v247, v247, v251, vcc
	    v_mul_f32_e32 v244, v246, v244
	    v_mul_f32_e32 v245, v247, v245
	    v_mul_f32_e32 v244, v184, v244
	    v_mul_f32_e32 v245, v185, v245
	    v_bfe_u32 v250, v244, 16, 1
	    v_bfe_u32 v251, v245, 16, 1
	    v_add3_u32 v244, v244, v250, s49
	    v_add3_u32 v245, v245, v251, s49
	    v_perm_b32 v20, v245, v244, v194
	    global_store_dword v[202:203], v20, off offset:256
	s_cmpk_eq_i32 s57, 0x50
	s_cbranch_scc1 .Lkn5_s_237_1_1
	s_waitcnt vmcnt(20)
	s_branch .Lkn5_e_237_1_1

; __device__ __forceinline__ float bf2f(unsigned short u) { return __uint_as_float((unsigned)u << 16); }
; __device__ __forceinline__ unsigned f2bf(float f) { unsigned u = __float_as_uint(f); return (u + 0x7fffu + ((u >> 16) & 1u)) >> 16; }
; __device__ __forceinline__ void knorm_item(const KArgs& a, int l, int item, int wave, int lane) {
;     ...
;     for (int r0 = 0; r0 < 128; r0 += 16) {
;         float v[16];
; #pragma unroll
;         for (int i = 0; i < 16; ++i) { const int task = item * 1024 + wave * 128 + r0 + i, row = task >> 2, which = (task >> 1) & 1, g = task & 1;
;             v[i] = bf2f(Z[(size_t)row * ZW + (which ? ZC_KW : ZC_KS) + g * 64 + lane]); }
; #pragma unroll
;         for (int i = 0; i < 16; ++i) { const int task = item * 1024 + wave * 128 + r0 + i, row = task >> 2, which = (task >> 1) & 1, g = task & 1;
;             const float rstd = rsqrtf(wave_sum(v[i] * v[i]) * (1.f / 64.f) + EPS);
;             bf16_t* dst = (bf16_t*)(a.ws + (which ? WS_KWN : WS_KSN));
;             dst[(size_t)row * 128 + g * 64 + lane] = (bf16_t)f2bf(v[i] * rstd * kg); }
.Lkn5_e_237_1_1:
	v_lshlrev_b32_e32 v220, 16, v17
	v_and_b32_e32 v221, 0xffff0000, v17
	v_lshlrev_b32_e32 v228, 16, v18
	v_and_b32_e32 v229, 0xffff0000, v18
	v_lshlrev_b32_e32 v236, 16, v15
	v_and_b32_e32 v237, 0xffff0000, v15
	v_lshlrev_b32_e32 v244, 16, v16
	v_and_b32_e32 v245, 0xffff0000, v16
	v_mul_f32_e32 v224, v220, v220
	v_mul_f32_e32 v225, v221, v221
	v_mul_f32_e32 v232, v228, v228
	v_mul_f32_e32 v233, v229, v229
	v_mul_f32_e32 v240, v236, v236
	v_mul_f32_e32 v241, v237, v237
	v_mul_f32_e32 v248, v244, v244
	v_mul_f32_e32 v249, v245, v245
	v_fma_f32 v222, v220, v220, v225
	v_fma_f32 v223, v221, v221, v224
	v_fma_f32 v230, v228, v228, v233
	v_fma_f32 v231, v229, v229, v232
	v_fma_f32 v238, v236, v236, v241
	v_fma_f32 v239, v237, v237, v240
	v_fma_f32 v246, v244, v244, v249
	v_fma_f32 v247, v245, v245, v248
	v_add_f32_dpp v222, v222, v222 quad_perm:[1,0,3,2] row_mask:0xf bank_mask:0xf
	v_add_f32_dpp v223, v223, v223 quad_perm:[1,0,3,2] row_mask:0xf bank_mask:0xf
	v_add_f32_dpp v230, v230, v230 quad_perm:[1,0,3,2] row_mask:0xf bank_mask:0xf
	v_add_f32_dpp v231, v231, v231 quad_perm:[1,0,3,2] row_mask:0xf bank_mask:0xf
	v_add_f32_dpp v238, v238, v238 quad_perm:[1,0,3,2] row_mask:0xf bank_mask:0xf
	v_add_f32_dpp v239, v239, v239 quad_perm:[1,0,3,2] row_mask:0xf bank_mask:0xf
	v_add_f32_dpp v246, v246, v246 quad_perm:[1,0,3,2] row_mask:0xf bank_mask:0xf
	v_add_f32_dpp v247, v247, v247 quad_perm:[1,0,3,2] row_mask:0xf bank_mask:0xf
	v_add_f32_dpp v222, v222, v222 quad_perm:[2,3,0,1] row_mask:0xf bank_mask:0xf
	v_add_f32_dpp v223, v223, v223 quad_perm:[2,3,0,1] row_mask:0xf bank_mask:0xf
	v_add_f32_dpp v230, v230, v230 quad_perm:[2,3,0,1] row_mask:0xf bank_mask:0xf
	v_add_f32_dpp v231, v231, v231 quad_perm:[2,3,0,1] row_mask:0xf bank_mask:0xf
	v_add_f32_dpp v238, v238, v238 quad_perm:[2,3,0,1] row_mask:0xf bank_mask:0xf
	v_add_f32_dpp v239, v239, v239 quad_perm:[2,3,0,1] row_mask:0xf bank_mask:0xf
	v_add_f32_dpp v246, v246, v246 quad_perm:[2,3,0,1] row_mask:0xf bank_mask:0xf
	v_add_f32_dpp v247, v247, v247 quad_perm:[2,3,0,1] row_mask:0xf bank_mask:0xf
	ds_bpermute_b32 v224, v11, v222
	ds_bpermute_b32 v225, v11, v223
	ds_bpermute_b32 v232, v11, v230
	ds_bpermute_b32 v233, v11, v231
	ds_bpermute_b32 v240, v11, v238
	ds_bpermute_b32 v241, v11, v239
	ds_bpermute_b32 v248, v11, v246
	ds_bpermute_b32 v249, v11, v247
	s_waitcnt lgkmcnt(0)
	v_add_f32_e32 v222, v222, v224
	v_add_f32_e32 v223, v223, v225
	v_add_f32_e32 v230, v230, v232
	v_add_f32_e32 v231, v231, v233
	v_add_f32_e32 v238, v238, v240
	v_add_f32_e32 v239, v239, v241
	v_add_f32_e32 v246, v246, v248
	v_add_f32_e32 v247, v247, v249
	v_add_f32_dpp v222, v222, v222 row_ror:8 row_mask:0xf bank_mask:0xf
	v_add_f32_dpp v223, v223, v223 row_ror:8 row_mask:0xf bank_mask:0xf
	v_add_f32_dpp v230, v230, v230 row_ror:8 row_mask:0xf bank_mask:0xf
	v_add_f32_dpp v231, v231, v231 row_ror:8 row_mask:0xf bank_mask:0xf
	v_add_f32_dpp v238, v238, v238 row_ror:8 row_mask:0xf bank_mask:0xf
	v_add_f32_dpp v239, v239, v239 row_ror:8 row_mask:0xf bank_mask:0xf
	v_add_f32_dpp v246, v246, v246 row_ror:8 row_mask:0xf bank_mask:0xf
	v_add_f32_dpp v247, v247, v247 row_ror:8 row_mask:0xf bank_mask:0xf
	ds_bpermute_b32 v224, v13, v222
	ds_bpermute_b32 v225, v13, v223
	ds_bpermute_b32 v232, v13, v230
	ds_bpermute_b32 v233, v13, v231
	ds_bpermute_b32 v240, v13, v238
	ds_bpermute_b32 v241, v13, v239
	ds_bpermute_b32 v248, v13, v246
	ds_bpermute_b32 v249, v13, v247
	s_waitcnt lgkmcnt(0)
; __device__ __forceinline__ float bf2f(unsigned short u) { return __uint_as_float((unsigned)u << 16); }
; __device__ __forceinline__ unsigned f2bf(float f) { unsigned u = __float_as_uint(f); return (u + 0x7fffu + ((u >> 16) & 1u)) >> 16; }
; __device__ __forceinline__ void knorm_item(const KArgs& a, int l, int item, int wave, int lane) {
;     ...
;     for (int r0 = 0; r0 < 128; r0 += 16) {
;         float v[16];
; #pragma unroll
;         for (int i = 0; i < 16; ++i) { const int task = item * 1024 + wave * 128 + r0 + i, row = task >> 2, which = (task >> 1) & 1, g = task & 1;
;             v[i] = bf2f(Z[(size_t)row * ZW + (which ? ZC_KW : ZC_KS) + g * 64 + lane]); }
; #pragma unroll
;         for (int i = 0; i < 16; ++i) { const int task = item * 1024 + wave * 128 + r0 + i, row = task >> 2, which = (task >> 1) & 1, g = task & 1;
;             const float rstd = rsqrtf(wave_sum(v[i] * v[i]) * (1.f / 64.f) + EPS);
;             bf16_t* dst = (bf16_t*)(a.ws + (which ? WS_KWN : WS_KSN));
;             dst[(size_t)row * 128 + g * 64 + lane] = (bf16_t)f2bf(v[i] * rstd * kg); }
	v_add_f32_e32 v222, v222, v224
	v_add_f32_e32 v223, v223, v225
	v_add_f32_e32 v230, v230, v232
	v_add_f32_e32 v231, v231, v233
	v_add_f32_e32 v238, v238, v240
	v_add_f32_e32 v239, v239, v241
	v_add_f32_e32 v246, v246, v248
	v_add_f32_e32 v247, v247, v249
	v_fma_f32 v222, v222, s22, v195
	v_fma_f32 v223, v223, s22, v195
	v_fma_f32 v230, v230, s22, v195
	v_fma_f32 v231, v231, s22, v195
	v_fma_f32 v238, v238, s22, v195
	v_fma_f32 v239, v239, s22, v195
	v_fma_f32 v246, v246, s22, v195
	v_fma_f32 v247, v247, s22, v195
	v_mul_f32_e32 v226, 0x4b800000, v222
	    v_mul_f32_e32 v227, 0x4b800000, v223
	    v_cmp_gt_f32_e64 s[4:5], s48, v222
	    v_cmp_gt_f32_e32 vcc, s48, v223
	    s_nop 1
	    v_cndmask_b32_e64 v222, v222, v226, s[4:5]
	    v_cndmask_b32_e32 v223, v223, v227, vcc
	    v_rsq_f32_e32 v222, v222
	    v_rsq_f32_e32 v223, v223
	    s_nop 0
	    v_mul_f32_e32 v226, 0x45800000, v222
	    v_mul_f32_e32 v227, 0x45800000, v223
	    v_cndmask_b32_e64 v222, v222, v226, s[4:5]
	    v_cndmask_b32_e32 v223, v223, v227, vcc
	    v_mul_f32_e32 v220, v222, v220
	    v_mul_f32_e32 v221, v223, v221
	    v_mul_f32_e32 v220, v184, v220
	    v_mul_f32_e32 v221, v185, v221
	    v_bfe_u32 v226, v220, 16, 1
	    v_bfe_u32 v227, v221, 16, 1
	    v_add3_u32 v220, v220, v226, s49
	    v_add3_u32 v221, v221, v227, s49
	    v_perm_b32 v17, v221, v220, v194
	    global_store_dword v[200:201], v17, off offset:512
	v_mul_f32_e32 v234, 0x4b800000, v230
	    v_mul_f32_e32 v235, 0x4b800000, v231
	    v_cmp_gt_f32_e64 s[4:5], s48, v230
	    v_cmp_gt_f32_e32 vcc, s48, v231
	    s_nop 1
	    v_cndmask_b32_e64 v230, v230, v234, s[4:5]
	    v_cndmask_b32_e32 v231, v231, v235, vcc
	    v_rsq_f32_e32 v230, v230
	    v_rsq_f32_e32 v231, v231
	    s_nop 0
	    v_mul_f32_e32 v234, 0x45800000, v230
	    v_mul_f32_e32 v235, 0x45800000, v231
	    v_cndmask_b32_e64 v230, v230, v234, s[4:5]
	    v_cndmask_b32_e32 v231, v231, v235, vcc
	    v_mul_f32_e32 v228, v230, v228
	    v_mul_f32_e32 v229, v231, v229
	    v_mul_f32_e32 v228, v184, v228
	    v_mul_f32_e32 v229, v185, v229
	    v_bfe_u32 v234, v228, 16, 1
	    v_bfe_u32 v235, v229, 16, 1
	    v_add3_u32 v228, v228, v234, s49
	    v_add3_u32 v229, v229, v235, s49
	    v_perm_b32 v18, v229, v228, v194
	    global_store_dword v[202:203], v18, off offset:512
	v_mul_f32_e32 v242, 0x4b800000, v238
	    v_mul_f32_e32 v243, 0x4b800000, v239
	    v_cmp_gt_f32_e64 s[4:5], s48, v238
	    v_cmp_gt_f32_e32 vcc, s48, v239
	    s_nop 1
	    v_cndmask_b32_e64 v238, v238, v242, s[4:5]
	    v_cndmask_b32_e32 v239, v239, v243, vcc
	    v_rsq_f32_e32 v238, v238
	    v_rsq_f32_e32 v239, v239
	    s_nop 0
	    v_mul_f32_e32 v242, 0x45800000, v238
	    v_mul_f32_e32 v243, 0x45800000, v239
	    v_cndmask_b32_e64 v238, v238, v242, s[4:5]
	    v_cndmask_b32_e32 v239, v239, v243, vcc
	    v_mul_f32_e32 v236, v238, v236
	    v_mul_f32_e32 v237, v239, v237
	    v_mul_f32_e32 v236, v184, v236
	    v_mul_f32_e32 v237, v185, v237
	    v_bfe_u32 v242, v236, 16, 1
	    v_bfe_u32 v243, v237, 16, 1
	    v_add3_u32 v236, v236, v242, s49
	    v_add3_u32 v237, v237, v243, s49
	    v_perm_b32 v15, v237, v236, v194
	    global_store_dword v[200:201], v15, off offset:768
	v_mul_f32_e32 v250, 0x4b800000, v246
	    v_mul_f32_e32 v251, 0x4b800000, v247
	    v_cmp_gt_f32_e64 s[4:5], s48, v246
	    v_cmp_gt_f32_e32 vcc, s48, v247
	    s_nop 1
	    v_cndmask_b32_e64 v246, v246, v250, s[4:5]
	    v_cndmask_b32_e32 v247, v247, v251, vcc
	    v_rsq_f32_e32 v246, v246
	    v_rsq_f32_e32 v247, v247
	    s_nop 0
	    v_mul_f32_e32 v250, 0x45800000, v246
	    v_mul_f32_e32 v251, 0x45800000, v247
	    v_cndmask_b32_e64 v246, v246, v250, s[4:5]
	    v_cndmask_b32_e32 v247, v247, v251, vcc
	    v_mul_f32_e32 v244, v246, v244
	    v_mul_f32_e32 v245, v247, v245
	    v_mul_f32_e32 v244, v184, v244
	    v_mul_f32_e32 v245, v185, v245
	    v_bfe_u32 v250, v244, 16, 1
	    v_bfe_u32 v251, v245, 16, 1
	    v_add3_u32 v244, v244, v250, s49
	    v_add3_u32 v245, v245, v251, s49
	    v_perm_b32 v16, v245, v244, v194
	    global_store_dword v[202:203], v16, off offset:768
	s_add_i32 s57, s57, 32
	s_cmpk_gt_u32 s57, 0x6f
	s_cbranch_scc0 .LBB0_237
	s_mov_b64 s[0:1], 0

; __device__ __forceinline__ float bf2f(unsigned short u) { return __uint_as_float((unsigned)u << 16); }
; __device__ __forceinline__ void knorm_item(const KArgs& a, int l, int item, int wave, int lane) {
;     ...
;     for (int r0 = 0; r0 < 128; r0 += 16) {
;         float v[16];
; #pragma unroll
;         for (int i = 0; i < 16; ++i) { const int task = item * 1024 + wave * 128 + r0 + i, row = task >> 2, which = (task >> 1) & 1, g = task & 1;
;             v[i] = bf2f(Z[(size_t)row * ZW + (which ? ZC_KW : ZC_KS) + g * 64 + lane]); }
.LBB0_1038:
	s_add_i32 s0, s30, s63
	s_add_i32 s0, s0, 0xfff80020
	s_ashr_i32 s4, s0, 2
	s_ashr_i32 s5, s4, 31
	s_mul_i32 s0, s4, 0x1a00
	s_mul_hi_i32 s1, s4, 0x1a00
	s_add_u32 s0, s92, s0
	s_addc_u32 s1, s93, s1
	v_lshl_add_u64 v[0:1], s[0:1], 0, v[196:197]
	global_load_dword v21, v[0:1], off offset:1024
	global_load_dword v22, v[0:1], off offset:1536
	s_add_u32 s0, s0, 0x1a00
	s_addc_u32 s1, s1, 0
	v_lshl_add_u64 v[2:3], s[0:1], 0, v[196:197]
	global_load_dword v19, v[2:3], off offset:1024
	global_load_dword v20, v[2:3], off offset:1536
	s_add_u32 s0, s0, 0x1a00
	s_addc_u32 s1, s1, 0
	v_lshl_add_u64 v[0:1], s[0:1], 0, v[196:197]
	global_load_dword v17, v[0:1], off offset:1024
	global_load_dword v18, v[0:1], off offset:1536
	s_add_u32 s0, s0, 0x1a00
	s_addc_u32 s1, s1, 0
	v_lshl_add_u64 v[2:3], s[0:1], 0, v[196:197]
	global_load_dword v15, v[2:3], off offset:1024
	global_load_dword v16, v[2:3], off offset:1536
	s_add_i32 s0, s30, s63
	s_add_i32 s0, s0, 0xfff80010
	s_ashr_i32 s4, s0, 2
	s_ashr_i32 s5, s4, 31
	s_lshl_b64 s[38:39], s[4:5], 8
	v_lshl_add_u64 v[200:201], v[190:191], 0, s[38:39]
	v_lshl_add_u64 v[202:203], v[192:193], 0, s[38:39]
	s_cmp_eq_i32 s63, -16
	s_cbranch_scc1 .Lkn5_s_1038_0_0
	s_waitcnt vmcnt(20)
	s_branch .Lkn5_e_1038_0_0

; __device__ __forceinline__ float bf2f(unsigned short u) { return __uint_as_float((unsigned)u << 16); }
; __device__ __forceinline__ void knorm_item(const KArgs& a, int l, int item, int wave, int lane) {
;     ...
;         for (int i = 0; i < 16; ++i) { const int task = item * 1024 + wave * 128 + r0 + i, row = task >> 2, which = (task >> 1) & 1, g = task & 1;
;             v[i] = bf2f(Z[(size_t)row * ZW + (which ? ZC_KW : ZC_KS) + g * 64 + lane]); }
; #pragma unroll
;         for (int i = 0; i < 16; ++i) { const int task = item * 1024 + wave * 128 + r0 + i, row = task >> 2, which = (task >> 1) & 1, g = task & 1;
;             const float rstd = rsqrtf(wave_sum(v[i] * v[i]) * (1.f / 64.f) + EPS);
.Lkn5_e_1038_0_0:
	v_lshlrev_b32_e32 v220, 16, v4
	v_and_b32_e32 v221, 0xffff0000, v4
	v_lshlrev_b32_e32 v228, 16, v6
	v_and_b32_e32 v229, 0xffff0000, v6
	v_lshlrev_b32_e32 v236, 16, v27
	v_and_b32_e32 v237, 0xffff0000, v27
	v_lshlrev_b32_e32 v244, 16, v28
	v_and_b32_e32 v245, 0xffff0000, v28
	v_mul_f32_e32 v224, v220, v220
	v_mul_f32_e32 v225, v221, v221
	v_mul_f32_e32 v232, v228, v228
	v_mul_f32_e32 v233, v229, v229
	v_mul_f32_e32 v240, v236, v236
	v_mul_f32_e32 v241, v237, v237
	v_mul_f32_e32 v248, v244, v244
	v_mul_f32_e32 v249, v245, v245
	v_fma_f32 v222, v220, v220, v225
	v_fma_f32 v223, v221, v221, v224
	v_fma_f32 v230, v228, v228, v233
	v_fma_f32 v231, v229, v229, v232
	v_fma_f32 v238, v236, v236, v241
	v_fma_f32 v239, v237, v237, v240
	v_fma_f32 v246, v244, v244, v249
	v_fma_f32 v247, v245, v245, v248
	v_add_f32_dpp v222, v222, v222 quad_perm:[1,0,3,2] row_mask:0xf bank_mask:0xf
	v_add_f32_dpp v223, v223, v223 quad_perm:[1,0,3,2] row_mask:0xf bank_mask:0xf
	v_add_f32_dpp v230, v230, v230 quad_perm:[1,0,3,2] row_mask:0xf bank_mask:0xf
	v_add_f32_dpp v231, v231, v231 quad_perm:[1,0,3,2] row_mask:0xf bank_mask:0xf
	v_add_f32_dpp v238, v238, v238 quad_perm:[1,0,3,2] row_mask:0xf bank_mask:0xf
	v_add_f32_dpp v239, v239, v239 quad_perm:[1,0,3,2] row_mask:0xf bank_mask:0xf
	v_add_f32_dpp v246, v246, v246 quad_perm:[1,0,3,2] row_mask:0xf bank_mask:0xf
	v_add_f32_dpp v247, v247, v247 quad_perm:[1,0,3,2] row_mask:0xf bank_mask:0xf
	v_add_f32_dpp v222, v222, v222 quad_perm:[2,3,0,1] row_mask:0xf bank_mask:0xf
	v_add_f32_dpp v223, v223, v223 quad_perm:[2,3,0,1] row_mask:0xf bank_mask:0xf
	v_add_f32_dpp v230, v230, v230 quad_perm:[2,3,0,1] row_mask:0xf bank_mask:0xf
	v_add_f32_dpp v231, v231, v231 quad_perm:[2,3,0,1] row_mask:0xf bank_mask:0xf
	v_add_f32_dpp v238, v238, v238 quad_perm:[2,3,0,1] row_mask:0xf bank_mask:0xf
	v_add_f32_dpp v239, v239, v239 quad_perm:[2,3,0,1] row_mask:0xf bank_mask:0xf
	v_add_f32_dpp v246, v246, v246 quad_perm:[2,3,0,1] row_mask:0xf bank_mask:0xf
	v_add_f32_dpp v247, v247, v247 quad_perm:[2,3,0,1] row_mask:0xf bank_mask:0xf
	ds_bpermute_b32 v224, v11, v222
	ds_bpermute_b32 v225, v11, v223
	ds_bpermute_b32 v232, v11, v230
	ds_bpermute_b32 v233, v11, v231
	ds_bpermute_b32 v240, v11, v238
	ds_bpermute_b32 v241, v11, v239
	ds_bpermute_b32 v248, v11, v246
	ds_bpermute_b32 v249, v11, v247
	s_waitcnt lgkmcnt(0)
	v_add_f32_e32 v222, v222, v224
	v_add_f32_e32 v223, v223, v225
	v_add_f32_e32 v230, v230, v232
	v_add_f32_e32 v231, v231, v233
	v_add_f32_e32 v238, v238, v240
	v_add_f32_e32 v239, v239, v241
	v_add_f32_e32 v246, v246, v248
	v_add_f32_e32 v247, v247, v249
	v_add_f32_dpp v222, v222, v222 row_ror:8 row_mask:0xf bank_mask:0xf
	v_add_f32_dpp v223, v223, v223 row_ror:8 row_mask:0xf bank_mask:0xf
	v_add_f32_dpp v230, v230, v230 row_ror:8 row_mask:0xf bank_mask:0xf
	v_add_f32_dpp v231, v231, v231 row_ror:8 row_mask:0xf bank_mask:0xf
	v_add_f32_dpp v238, v238, v238 row_ror:8 row_mask:0xf bank_mask:0xf
	v_add_f32_dpp v239, v239, v239 row_ror:8 row_mask:0xf bank_mask:0xf
	v_add_f32_dpp v246, v246, v246 row_ror:8 row_mask:0xf bank_mask:0xf
	v_add_f32_dpp v247, v247, v247 row_ror:8 row_mask:0xf bank_mask:0xf
	ds_bpermute_b32 v224, v13, v222
	ds_bpermute_b32 v225, v13, v223
	ds_bpermute_b32 v232, v13, v230
	ds_bpermute_b32 v233, v13, v231
	ds_bpermute_b32 v240, v13, v238
	ds_bpermute_b32 v241, v13, v239
	ds_bpermute_b32 v248, v13, v246
	ds_bpermute_b32 v249, v13, v247
	s_waitcnt lgkmcnt(0)
; __device__ __forceinline__ unsigned f2bf(float f) { unsigned u = __float_as_uint(f); return (u + 0x7fffu + ((u >> 16) & 1u)) >> 16; }
; __device__ __forceinline__ void knorm_item(const KArgs& a, int l, int item, int wave, int lane) {
;     ...
;         for (int i = 0; i < 16; ++i) { const int task = item * 1024 + wave * 128 + r0 + i, row = task >> 2, which = (task >> 1) & 1, g = task & 1;
;             const float rstd = rsqrtf(wave_sum(v[i] * v[i]) * (1.f / 64.f) + EPS);
;             bf16_t* dst = (bf16_t*)(a.ws + (which ? WS_KWN : WS_KSN));
;             dst[(size_t)row * 128 + g * 64 + lane] = (bf16_t)f2bf(v[i] * rstd * kg); }
	v_add_f32_e32 v222, v222, v224
	v_add_f32_e32 v223, v223, v225
	v_add_f32_e32 v230, v230, v232
	v_add_f32_e32 v231, v231, v233
	v_add_f32_e32 v238, v238, v240
	v_add_f32_e32 v239, v239, v241
	v_add_f32_e32 v246, v246, v248
	v_add_f32_e32 v247, v247, v249
	v_fma_f32 v222, v222, s28, v195
	v_fma_f32 v223, v223, s28, v195
	v_fma_f32 v230, v230, s28, v195
	v_fma_f32 v231, v231, s28, v195
	v_fma_f32 v238, v238, s28, v195
	v_fma_f32 v239, v239, s28, v195
	v_fma_f32 v246, v246, s28, v195
	v_fma_f32 v247, v247, s28, v195
	v_mul_f32_e32 v226, 0x4b800000, v222
	    v_mul_f32_e32 v227, 0x4b800000, v223
	    v_cmp_gt_f32_e64 s[4:5], s54, v222
	    v_cmp_gt_f32_e32 vcc, s54, v223
	    s_nop 1
	    v_cndmask_b32_e64 v222, v222, v226, s[4:5]
	    v_cndmask_b32_e32 v223, v223, v227, vcc
	    v_rsq_f32_e32 v222, v222
	    v_rsq_f32_e32 v223, v223
	    s_nop 0
	    v_mul_f32_e32 v226, 0x45800000, v222
	    v_mul_f32_e32 v227, 0x45800000, v223
	    v_cndmask_b32_e64 v222, v222, v226, s[4:5]
	    v_cndmask_b32_e32 v223, v223, v227, vcc
	    v_mul_f32_e32 v220, v222, v220
	    v_mul_f32_e32 v221, v223, v221
	    v_mul_f32_e32 v220, v184, v220
	    v_mul_f32_e32 v221, v185, v221
	    v_bfe_u32 v226, v220, 16, 1
	    v_bfe_u32 v227, v221, 16, 1
	    v_add3_u32 v220, v220, v226, s55
	    v_add3_u32 v221, v221, v227, s55
	    v_perm_b32 v4, v221, v220, v194
	    global_store_dword v[200:201], v4, off
	v_mul_f32_e32 v234, 0x4b800000, v230
	    v_mul_f32_e32 v235, 0x4b800000, v231
	    v_cmp_gt_f32_e64 s[4:5], s54, v230
	    v_cmp_gt_f32_e32 vcc, s54, v231
	    s_nop 1
	    v_cndmask_b32_e64 v230, v230, v234, s[4:5]
	    v_cndmask_b32_e32 v231, v231, v235, vcc
	    v_rsq_f32_e32 v230, v230
	    v_rsq_f32_e32 v231, v231
	    s_nop 0
	    v_mul_f32_e32 v234, 0x45800000, v230
	    v_mul_f32_e32 v235, 0x45800000, v231
	    v_cndmask_b32_e64 v230, v230, v234, s[4:5]
	    v_cndmask_b32_e32 v231, v231, v235, vcc
	    v_mul_f32_e32 v228, v230, v228
	    v_mul_f32_e32 v229, v231, v229
	    v_mul_f32_e32 v228, v184, v228
	    v_mul_f32_e32 v229, v185, v229
	    v_bfe_u32 v234, v228, 16, 1
	    v_bfe_u32 v235, v229, 16, 1
	    v_add3_u32 v228, v228, v234, s55
	    v_add3_u32 v229, v229, v235, s55
	    v_perm_b32 v6, v229, v228, v194
	    global_store_dword v[202:203], v6, off
	v_mul_f32_e32 v242, 0x4b800000, v238
	    v_mul_f32_e32 v243, 0x4b800000, v239
	    v_cmp_gt_f32_e64 s[4:5], s54, v238
	    v_cmp_gt_f32_e32 vcc, s54, v239
	    s_nop 1
	    v_cndmask_b32_e64 v238, v238, v242, s[4:5]
	    v_cndmask_b32_e32 v239, v239, v243, vcc
	    v_rsq_f32_e32 v238, v238
	    v_rsq_f32_e32 v239, v239
	    s_nop 0
	    v_mul_f32_e32 v242, 0x45800000, v238
	    v_mul_f32_e32 v243, 0x45800000, v239
	    v_cndmask_b32_e64 v238, v238, v242, s[4:5]
	    v_cndmask_b32_e32 v239, v239, v243, vcc
	    v_mul_f32_e32 v236, v238, v236
	    v_mul_f32_e32 v237, v239, v237
	    v_mul_f32_e32 v236, v184, v236
	    v_mul_f32_e32 v237, v185, v237
	    v_bfe_u32 v242, v236, 16, 1
	    v_bfe_u32 v243, v237, 16, 1
	    v_add3_u32 v236, v236, v242, s55
	    v_add3_u32 v237, v237, v243, s55
	    v_perm_b32 v27, v237, v236, v194
	    global_store_dword v[200:201], v27, off offset:256
	v_mul_f32_e32 v250, 0x4b800000, v246
	    v_mul_f32_e32 v251, 0x4b800000, v247
	    v_cmp_gt_f32_e64 s[4:5], s54, v246
	    v_cmp_gt_f32_e32 vcc, s54, v247
	    s_nop 1
	    v_cndmask_b32_e64 v246, v246, v250, s[4:5]
	    v_cndmask_b32_e32 v247, v247, v251, vcc
	    v_rsq_f32_e32 v246, v246
	    v_rsq_f32_e32 v247, v247
	    s_nop 0
	    v_mul_f32_e32 v250, 0x45800000, v246
	    v_mul_f32_e32 v251, 0x45800000, v247
	    v_cndmask_b32_e64 v246, v246, v250, s[4:5]
	    v_cndmask_b32_e32 v247, v247, v251, vcc
	    v_mul_f32_e32 v244, v246, v244
	    v_mul_f32_e32 v245, v247, v245
	    v_mul_f32_e32 v244, v184, v244
	    v_mul_f32_e32 v245, v185, v245
	    v_bfe_u32 v250, v244, 16, 1
	    v_bfe_u32 v251, v245, 16, 1
	    v_add3_u32 v244, v244, v250, s55
	    v_add3_u32 v245, v245, v251, s55
	    v_perm_b32 v28, v245, v244, v194
	    global_store_dword v[202:203], v28, off offset:256
	s_cmp_eq_i32 s63, -16
	s_cbranch_scc1 .Lkn5_s_1038_0_1
	s_waitcnt vmcnt(20)
	s_branch .Lkn5_e_1038_0_1

; __device__ __forceinline__ float bf2f(unsigned short u) { return __uint_as_float((unsigned)u << 16); }
; __device__ __forceinline__ void knorm_item(const KArgs& a, int l, int item, int wave, int lane) {
;     ...
;         for (int i = 0; i < 16; ++i) { const int task = item * 1024 + wave * 128 + r0 + i, row = task >> 2, which = (task >> 1) & 1, g = task & 1;
;             v[i] = bf2f(Z[(size_t)row * ZW + (which ? ZC_KW : ZC_KS) + g * 64 + lane]); }
; #pragma unroll
;         for (int i = 0; i < 16; ++i) { const int task = item * 1024 + wave * 128 + r0 + i, row = task >> 2, which = (task >> 1) & 1, g = task & 1;
;             const float rstd = rsqrtf(wave_sum(v[i] * v[i]) * (1.f / 64.f) + EPS);
.Lkn5_e_1038_0_1:
	v_lshlrev_b32_e32 v220, 16, v25
	v_and_b32_e32 v221, 0xffff0000, v25
	v_lshlrev_b32_e32 v228, 16, v26
	v_and_b32_e32 v229, 0xffff0000, v26
	v_lshlrev_b32_e32 v236, 16, v23
	v_and_b32_e32 v237, 0xffff0000, v23
	v_lshlrev_b32_e32 v244, 16, v24
	v_and_b32_e32 v245, 0xffff0000, v24
	v_mul_f32_e32 v224, v220, v220
	v_mul_f32_e32 v225, v221, v221
	v_mul_f32_e32 v232, v228, v228
	v_mul_f32_e32 v233, v229, v229
	v_mul_f32_e32 v240, v236, v236
	v_mul_f32_e32 v241, v237, v237
	v_mul_f32_e32 v248, v244, v244
	v_mul_f32_e32 v249, v245, v245
	v_fma_f32 v222, v220, v220, v225
	v_fma_f32 v223, v221, v221, v224
	v_fma_f32 v230, v228, v228, v233
	v_fma_f32 v231, v229, v229, v232
	v_fma_f32 v238, v236, v236, v241
	v_fma_f32 v239, v237, v237, v240
	v_fma_f32 v246, v244, v244, v249
	v_fma_f32 v247, v245, v245, v248
	v_add_f32_dpp v222, v222, v222 quad_perm:[1,0,3,2] row_mask:0xf bank_mask:0xf
	v_add_f32_dpp v223, v223, v223 quad_perm:[1,0,3,2] row_mask:0xf bank_mask:0xf
	v_add_f32_dpp v230, v230, v230 quad_perm:[1,0,3,2] row_mask:0xf bank_mask:0xf
	v_add_f32_dpp v231, v231, v231 quad_perm:[1,0,3,2] row_mask:0xf bank_mask:0xf
	v_add_f32_dpp v238, v238, v238 quad_perm:[1,0,3,2] row_mask:0xf bank_mask:0xf
	v_add_f32_dpp v239, v239, v239 quad_perm:[1,0,3,2] row_mask:0xf bank_mask:0xf
	v_add_f32_dpp v246, v246, v246 quad_perm:[1,0,3,2] row_mask:0xf bank_mask:0xf
	v_add_f32_dpp v247, v247, v247 quad_perm:[1,0,3,2] row_mask:0xf bank_mask:0xf
	v_add_f32_dpp v222, v222, v222 quad_perm:[2,3,0,1] row_mask:0xf bank_mask:0xf
	v_add_f32_dpp v223, v223, v223 quad_perm:[2,3,0,1] row_mask:0xf bank_mask:0xf
	v_add_f32_dpp v230, v230, v230 quad_perm:[2,3,0,1] row_mask:0xf bank_mask:0xf
	v_add_f32_dpp v231, v231, v231 quad_perm:[2,3,0,1] row_mask:0xf bank_mask:0xf
	v_add_f32_dpp v238, v238, v238 quad_perm:[2,3,0,1] row_mask:0xf bank_mask:0xf
	v_add_f32_dpp v239, v239, v239 quad_perm:[2,3,0,1] row_mask:0xf bank_mask:0xf
	v_add_f32_dpp v246, v246, v246 quad_perm:[2,3,0,1] row_mask:0xf bank_mask:0xf
	v_add_f32_dpp v247, v247, v247 quad_perm:[2,3,0,1] row_mask:0xf bank_mask:0xf
	ds_bpermute_b32 v224, v11, v222
	ds_bpermute_b32 v225, v11, v223
	ds_bpermute_b32 v232, v11, v230
	ds_bpermute_b32 v233, v11, v231
	ds_bpermute_b32 v240, v11, v238
	ds_bpermute_b32 v241, v11, v239
	ds_bpermute_b32 v248, v11, v246
	ds_bpermute_b32 v249, v11, v247
	s_waitcnt lgkmcnt(0)
	v_add_f32_e32 v222, v222, v224
	v_add_f32_e32 v223, v223, v225
	v_add_f32_e32 v230, v230, v232
	v_add_f32_e32 v231, v231, v233
	v_add_f32_e32 v238, v238, v240
	v_add_f32_e32 v239, v239, v241
	v_add_f32_e32 v246, v246, v248
	v_add_f32_e32 v247, v247, v249
	v_add_f32_dpp v222, v222, v222 row_ror:8 row_mask:0xf bank_mask:0xf
	v_add_f32_dpp v223, v223, v223 row_ror:8 row_mask:0xf bank_mask:0xf
	v_add_f32_dpp v230, v230, v230 row_ror:8 row_mask:0xf bank_mask:0xf
	v_add_f32_dpp v231, v231, v231 row_ror:8 row_mask:0xf bank_mask:0xf
	v_add_f32_dpp v238, v238, v238 row_ror:8 row_mask:0xf bank_mask:0xf
	v_add_f32_dpp v239, v239, v239 row_ror:8 row_mask:0xf bank_mask:0xf
	v_add_f32_dpp v246, v246, v246 row_ror:8 row_mask:0xf bank_mask:0xf
	v_add_f32_dpp v247, v247, v247 row_ror:8 row_mask:0xf bank_mask:0xf
	ds_bpermute_b32 v224, v13, v222
	ds_bpermute_b32 v225, v13, v223
	ds_bpermute_b32 v232, v13, v230
	ds_bpermute_b32 v233, v13, v231
	ds_bpermute_b32 v240, v13, v238
	ds_bpermute_b32 v241, v13, v239
	ds_bpermute_b32 v248, v13, v246
	ds_bpermute_b32 v249, v13, v247
	s_waitcnt lgkmcnt(0)
; __device__ __forceinline__ float bf2f(unsigned short u) { return __uint_as_float((unsigned)u << 16); }
; __device__ __forceinline__ unsigned f2bf(float f) { unsigned u = __float_as_uint(f); return (u + 0x7fffu + ((u >> 16) & 1u)) >> 16; }
; __device__ __forceinline__ void knorm_item(const KArgs& a, int l, int item, int wave, int lane) {
;     ...
;     for (int r0 = 0; r0 < 128; r0 += 16) {
;         float v[16];
; #pragma unroll
;         for (int i = 0; i < 16; ++i) { const int task = item * 1024 + wave * 128 + r0 + i, row = task >> 2, which = (task >> 1) & 1, g = task & 1;
;             v[i] = bf2f(Z[(size_t)row * ZW + (which ? ZC_KW : ZC_KS) + g * 64 + lane]); }
; #pragma unroll
;         for (int i = 0; i < 16; ++i) { const int task = item * 1024 + wave * 128 + r0 + i, row = task >> 2, which = (task >> 1) & 1, g = task & 1;
;             const float rstd = rsqrtf(wave_sum(v[i] * v[i]) * (1.f / 64.f) + EPS);
;             bf16_t* dst = (bf16_t*)(a.ws + (which ? WS_KWN : WS_KSN));
;             dst[(size_t)row * 128 + g * 64 + lane] = (bf16_t)f2bf(v[i] * rstd * kg); }
	v_add_f32_e32 v222, v222, v224
	v_add_f32_e32 v223, v223, v225
	v_add_f32_e32 v230, v230, v232
	v_add_f32_e32 v231, v231, v233
	v_add_f32_e32 v238, v238, v240
	v_add_f32_e32 v239, v239, v241
	v_add_f32_e32 v246, v246, v248
	v_add_f32_e32 v247, v247, v249
	v_fma_f32 v222, v222, s28, v195
	v_fma_f32 v223, v223, s28, v195
	v_fma_f32 v230, v230, s28, v195
	v_fma_f32 v231, v231, s28, v195
	v_fma_f32 v238, v238, s28, v195
	v_fma_f32 v239, v239, s28, v195
	v_fma_f32 v246, v246, s28, v195
	v_fma_f32 v247, v247, s28, v195
	v_mul_f32_e32 v226, 0x4b800000, v222
	    v_mul_f32_e32 v227, 0x4b800000, v223
	    v_cmp_gt_f32_e64 s[4:5], s54, v222
	    v_cmp_gt_f32_e32 vcc, s54, v223
	    s_nop 1
	    v_cndmask_b32_e64 v222, v222, v226, s[4:5]
	    v_cndmask_b32_e32 v223, v223, v227, vcc
	    v_rsq_f32_e32 v222, v222
	    v_rsq_f32_e32 v223, v223
	    s_nop 0
	    v_mul_f32_e32 v226, 0x45800000, v222
	    v_mul_f32_e32 v227, 0x45800000, v223
	    v_cndmask_b32_e64 v222, v222, v226, s[4:5]
	    v_cndmask_b32_e32 v223, v223, v227, vcc
	    v_mul_f32_e32 v220, v222, v220
	    v_mul_f32_e32 v221, v223, v221
	    v_mul_f32_e32 v220, v184, v220
	    v_mul_f32_e32 v221, v185, v221
	    v_bfe_u32 v226, v220, 16, 1
	    v_bfe_u32 v227, v221, 16, 1
	    v_add3_u32 v220, v220, v226, s55
	    v_add3_u32 v221, v221, v227, s55
	    v_perm_b32 v25, v221, v220, v194
	    global_store_dword v[200:201], v25, off offset:512
	v_mul_f32_e32 v234, 0x4b800000, v230
	    v_mul_f32_e32 v235, 0x4b800000, v231
	    v_cmp_gt_f32_e64 s[4:5], s54, v230
	    v_cmp_gt_f32_e32 vcc, s54, v231
	    s_nop 1
	    v_cndmask_b32_e64 v230, v230, v234, s[4:5]
	    v_cndmask_b32_e32 v231, v231, v235, vcc
	    v_rsq_f32_e32 v230, v230
	    v_rsq_f32_e32 v231, v231
	    s_nop 0
	    v_mul_f32_e32 v234, 0x45800000, v230
	    v_mul_f32_e32 v235, 0x45800000, v231
	    v_cndmask_b32_e64 v230, v230, v234, s[4:5]
	    v_cndmask_b32_e32 v231, v231, v235, vcc
	    v_mul_f32_e32 v228, v230, v228
	    v_mul_f32_e32 v229, v231, v229
	    v_mul_f32_e32 v228, v184, v228
	    v_mul_f32_e32 v229, v185, v229
	    v_bfe_u32 v234, v228, 16, 1
	    v_bfe_u32 v235, v229, 16, 1
	    v_add3_u32 v228, v228, v234, s55
	    v_add3_u32 v229, v229, v235, s55
	    v_perm_b32 v26, v229, v228, v194
	    global_store_dword v[202:203], v26, off offset:512
	v_mul_f32_e32 v242, 0x4b800000, v238
	    v_mul_f32_e32 v243, 0x4b800000, v239
	    v_cmp_gt_f32_e64 s[4:5], s54, v238
	    v_cmp_gt_f32_e32 vcc, s54, v239
	    s_nop 1
	    v_cndmask_b32_e64 v238, v238, v242, s[4:5]
	    v_cndmask_b32_e32 v239, v239, v243, vcc
	    v_rsq_f32_e32 v238, v238
	    v_rsq_f32_e32 v239, v239
	    s_nop 0
	    v_mul_f32_e32 v242, 0x45800000, v238
	    v_mul_f32_e32 v243, 0x45800000, v239
	    v_cndmask_b32_e64 v238, v238, v242, s[4:5]
	    v_cndmask_b32_e32 v239, v239, v243, vcc
	    v_mul_f32_e32 v236, v238, v236
	    v_mul_f32_e32 v237, v239, v237
	    v_mul_f32_e32 v236, v184, v236
	    v_mul_f32_e32 v237, v185, v237
	    v_bfe_u32 v242, v236, 16, 1
	    v_bfe_u32 v243, v237, 16, 1
	    v_add3_u32 v236, v236, v242, s55
	    v_add3_u32 v237, v237, v243, s55
	    v_perm_b32 v23, v237, v236, v194
	    global_store_dword v[200:201], v23, off offset:768
	v_mul_f32_e32 v250, 0x4b800000, v246
	    v_mul_f32_e32 v251, 0x4b800000, v247
	    v_cmp_gt_f32_e64 s[4:5], s54, v246
	    v_cmp_gt_f32_e32 vcc, s54, v247
	    s_nop 1
	    v_cndmask_b32_e64 v246, v246, v250, s[4:5]
	    v_cndmask_b32_e32 v247, v247, v251, vcc
	    v_rsq_f32_e32 v246, v246
	    v_rsq_f32_e32 v247, v247
	    s_nop 0
	    v_mul_f32_e32 v250, 0x45800000, v246
	    v_mul_f32_e32 v251, 0x45800000, v247
	    v_cndmask_b32_e64 v246, v246, v250, s[4:5]
	    v_cndmask_b32_e32 v247, v247, v251, vcc
	    v_mul_f32_e32 v244, v246, v244
	    v_mul_f32_e32 v245, v247, v245
	    v_mul_f32_e32 v244, v184, v244
	    v_mul_f32_e32 v245, v185, v245
	    v_bfe_u32 v250, v244, 16, 1
	    v_bfe_u32 v251, v245, 16, 1
	    v_add3_u32 v244, v244, v250, s55
	    v_add3_u32 v245, v245, v251, s55
	    v_perm_b32 v24, v245, v244, v194
	    global_store_dword v[202:203], v24, off offset:768
	s_cmpk_gt_i32 s63, 64
	s_cbranch_scc1 .Lkn5_skip_1038
	s_add_i32 s0, s30, s63
	s_add_i32 s0, s0, 0xfff80030
	s_ashr_i32 s4, s0, 2
	s_ashr_i32 s5, s4, 31
	s_mul_i32 s0, s4, 0x1a00
	s_mul_hi_i32 s1, s4, 0x1a00
	s_add_u32 s0, s92, s0
	s_addc_u32 s1, s93, s1
	v_lshl_add_u64 v[0:1], s[0:1], 0, v[196:197]
	global_load_dword v4, v[0:1], off offset:1024
	global_load_dword v6, v[0:1], off offset:1536
	s_add_u32 s0, s0, 0x1a00
	s_addc_u32 s1, s1, 0
	v_lshl_add_u64 v[2:3], s[0:1], 0, v[196:197]
	global_load_dword v27, v[2:3], off offset:1024
	global_load_dword v28, v[2:3], off offset:1536
	s_add_u32 s0, s0, 0x1a00
	s_addc_u32 s1, s1, 0
	v_lshl_add_u64 v[0:1], s[0:1], 0, v[196:197]
	global_load_dword v25, v[0:1], off offset:1024
	global_load_dword v26, v[0:1], off offset:1536
	s_add_u32 s0, s0, 0x1a00
	s_addc_u32 s1, s1, 0
	v_lshl_add_u64 v[2:3], s[0:1], 0, v[196:197]
	global_load_dword v23, v[2:3], off offset:1024
	global_load_dword v24, v[2:3], off offset:1536
.Lkn5_skip_1038:
	s_add_i32 s0, s30, s63
	s_add_i32 s0, s0, 0xfff80020
	s_ashr_i32 s4, s0, 2
	s_ashr_i32 s5, s4, 31
	s_lshl_b64 s[38:39], s[4:5], 8
	v_lshl_add_u64 v[200:201], v[190:191], 0, s[38:39]
	v_lshl_add_u64 v[202:203], v[192:193], 0, s[38:39]
	s_cmpk_eq_i32 s63, 0x50
	s_cbranch_scc1 .Lkn5_s_1038_1_0
	s_waitcnt vmcnt(20)
	s_branch .Lkn5_e_1038_1_0

; __device__ __forceinline__ float bf2f(unsigned short u) { return __uint_as_float((unsigned)u << 16); }
; __device__ __forceinline__ void knorm_item(const KArgs& a, int l, int item, int wave, int lane) {
;     ...
;         for (int i = 0; i < 16; ++i) { const int task = item * 1024 + wave * 128 + r0 + i, row = task >> 2, which = (task >> 1) & 1, g = task & 1;
;             v[i] = bf2f(Z[(size_t)row * ZW + (which ? ZC_KW : ZC_KS) + g * 64 + lane]); }
; #pragma unroll
;         for (int i = 0; i < 16; ++i) { const int task = item * 1024 + wave * 128 + r0 + i, row = task >> 2, which = (task >> 1) & 1, g = task & 1;
;             const float rstd = rsqrtf(wave_sum(v[i] * v[i]) * (1.f / 64.f) + EPS);
.Lkn5_e_1038_1_0:
	v_lshlrev_b32_e32 v220, 16, v21
	v_and_b32_e32 v221, 0xffff0000, v21
	v_lshlrev_b32_e32 v228, 16, v22
	v_and_b32_e32 v229, 0xffff0000, v22
	v_lshlrev_b32_e32 v236, 16, v19
	v_and_b32_e32 v237, 0xffff0000, v19
	v_lshlrev_b32_e32 v244, 16, v20
	v_and_b32_e32 v245, 0xffff0000, v20
	v_mul_f32_e32 v224, v220, v220
	v_mul_f32_e32 v225, v221, v221
	v_mul_f32_e32 v232, v228, v228
	v_mul_f32_e32 v233, v229, v229
	v_mul_f32_e32 v240, v236, v236
	v_mul_f32_e32 v241, v237, v237
	v_mul_f32_e32 v248, v244, v244
	v_mul_f32_e32 v249, v245, v245
	v_fma_f32 v222, v220, v220, v225
	v_fma_f32 v223, v221, v221, v224
	v_fma_f32 v230, v228, v228, v233
	v_fma_f32 v231, v229, v229, v232
	v_fma_f32 v238, v236, v236, v241
	v_fma_f32 v239, v237, v237, v240
	v_fma_f32 v246, v244, v244, v249
	v_fma_f32 v247, v245, v245, v248
	v_add_f32_dpp v222, v222, v222 quad_perm:[1,0,3,2] row_mask:0xf bank_mask:0xf
	v_add_f32_dpp v223, v223, v223 quad_perm:[1,0,3,2] row_mask:0xf bank_mask:0xf
	v_add_f32_dpp v230, v230, v230 quad_perm:[1,0,3,2] row_mask:0xf bank_mask:0xf
	v_add_f32_dpp v231, v231, v231 quad_perm:[1,0,3,2] row_mask:0xf bank_mask:0xf
	v_add_f32_dpp v238, v238, v238 quad_perm:[1,0,3,2] row_mask:0xf bank_mask:0xf
	v_add_f32_dpp v239, v239, v239 quad_perm:[1,0,3,2] row_mask:0xf bank_mask:0xf
	v_add_f32_dpp v246, v246, v246 quad_perm:[1,0,3,2] row_mask:0xf bank_mask:0xf
	v_add_f32_dpp v247, v247, v247 quad_perm:[1,0,3,2] row_mask:0xf bank_mask:0xf
	v_add_f32_dpp v222, v222, v222 quad_perm:[2,3,0,1] row_mask:0xf bank_mask:0xf
	v_add_f32_dpp v223, v223, v223 quad_perm:[2,3,0,1] row_mask:0xf bank_mask:0xf
	v_add_f32_dpp v230, v230, v230 quad_perm:[2,3,0,1] row_mask:0xf bank_mask:0xf
	v_add_f32_dpp v231, v231, v231 quad_perm:[2,3,0,1] row_mask:0xf bank_mask:0xf
	v_add_f32_dpp v238, v238, v238 quad_perm:[2,3,0,1] row_mask:0xf bank_mask:0xf
	v_add_f32_dpp v239, v239, v239 quad_perm:[2,3,0,1] row_mask:0xf bank_mask:0xf
	v_add_f32_dpp v246, v246, v246 quad_perm:[2,3,0,1] row_mask:0xf bank_mask:0xf
	v_add_f32_dpp v247, v247, v247 quad_perm:[2,3,0,1] row_mask:0xf bank_mask:0xf
	ds_bpermute_b32 v224, v11, v222
	ds_bpermute_b32 v225, v11, v223
	ds_bpermute_b32 v232, v11, v230
	ds_bpermute_b32 v233, v11, v231
	ds_bpermute_b32 v240, v11, v238
	ds_bpermute_b32 v241, v11, v239
	ds_bpermute_b32 v248, v11, v246
	ds_bpermute_b32 v249, v11, v247
	s_waitcnt lgkmcnt(0)
	v_add_f32_e32 v222, v222, v224
	v_add_f32_e32 v223, v223, v225
	v_add_f32_e32 v230, v230, v232
	v_add_f32_e32 v231, v231, v233
	v_add_f32_e32 v238, v238, v240
	v_add_f32_e32 v239, v239, v241
	v_add_f32_e32 v246, v246, v248
	v_add_f32_e32 v247, v247, v249
	v_add_f32_dpp v222, v222, v222 row_ror:8 row_mask:0xf bank_mask:0xf
	v_add_f32_dpp v223, v223, v223 row_ror:8 row_mask:0xf bank_mask:0xf
	v_add_f32_dpp v230, v230, v230 row_ror:8 row_mask:0xf bank_mask:0xf
	v_add_f32_dpp v231, v231, v231 row_ror:8 row_mask:0xf bank_mask:0xf
	v_add_f32_dpp v238, v238, v238 row_ror:8 row_mask:0xf bank_mask:0xf
	v_add_f32_dpp v239, v239, v239 row_ror:8 row_mask:0xf bank_mask:0xf
	v_add_f32_dpp v246, v246, v246 row_ror:8 row_mask:0xf bank_mask:0xf
	v_add_f32_dpp v247, v247, v247 row_ror:8 row_mask:0xf bank_mask:0xf
	ds_bpermute_b32 v224, v13, v222
	ds_bpermute_b32 v225, v13, v223
	ds_bpermute_b32 v232, v13, v230
	ds_bpermute_b32 v233, v13, v231
	ds_bpermute_b32 v240, v13, v238
	ds_bpermute_b32 v241, v13, v239
	ds_bpermute_b32 v248, v13, v246
	ds_bpermute_b32 v249, v13, v247
	s_waitcnt lgkmcnt(0)
; __device__ __forceinline__ unsigned f2bf(float f) { unsigned u = __float_as_uint(f); return (u + 0x7fffu + ((u >> 16) & 1u)) >> 16; }
; __device__ __forceinline__ void knorm_item(const KArgs& a, int l, int item, int wave, int lane) {
;     ...
;         for (int i = 0; i < 16; ++i) { const int task = item * 1024 + wave * 128 + r0 + i, row = task >> 2, which = (task >> 1) & 1, g = task & 1;
;             const float rstd = rsqrtf(wave_sum(v[i] * v[i]) * (1.f / 64.f) + EPS);
;             bf16_t* dst = (bf16_t*)(a.ws + (which ? WS_KWN : WS_KSN));
;             dst[(size_t)row * 128 + g * 64 + lane] = (bf16_t)f2bf(v[i] * rstd * kg); }
	v_add_f32_e32 v222, v222, v224
	v_add_f32_e32 v223, v223, v225
	v_add_f32_e32 v230, v230, v232
	v_add_f32_e32 v231, v231, v233
	v_add_f32_e32 v238, v238, v240
	v_add_f32_e32 v239, v239, v241
	v_add_f32_e32 v246, v246, v248
	v_add_f32_e32 v247, v247, v249
	v_fma_f32 v222, v222, s28, v195
	v_fma_f32 v223, v223, s28, v195
	v_fma_f32 v230, v230, s28, v195
	v_fma_f32 v231, v231, s28, v195
	v_fma_f32 v238, v238, s28, v195
	v_fma_f32 v239, v239, s28, v195
	v_fma_f32 v246, v246, s28, v195
	v_fma_f32 v247, v247, s28, v195
	v_mul_f32_e32 v226, 0x4b800000, v222
	    v_mul_f32_e32 v227, 0x4b800000, v223
	    v_cmp_gt_f32_e64 s[4:5], s54, v222
	    v_cmp_gt_f32_e32 vcc, s54, v223
	    s_nop 1
	    v_cndmask_b32_e64 v222, v222, v226, s[4:5]
	    v_cndmask_b32_e32 v223, v223, v227, vcc
	    v_rsq_f32_e32 v222, v222
	    v_rsq_f32_e32 v223, v223
	    s_nop 0
	    v_mul_f32_e32 v226, 0x45800000, v222
	    v_mul_f32_e32 v227, 0x45800000, v223
	    v_cndmask_b32_e64 v222, v222, v226, s[4:5]
	    v_cndmask_b32_e32 v223, v223, v227, vcc
	    v_mul_f32_e32 v220, v222, v220
	    v_mul_f32_e32 v221, v223, v221
	    v_mul_f32_e32 v220, v184, v220
	    v_mul_f32_e32 v221, v185, v221
	    v_bfe_u32 v226, v220, 16, 1
	    v_bfe_u32 v227, v221, 16, 1
	    v_add3_u32 v220, v220, v226, s55
	    v_add3_u32 v221, v221, v227, s55
	    v_perm_b32 v21, v221, v220, v194
	    global_store_dword v[200:201], v21, off
	v_mul_f32_e32 v234, 0x4b800000, v230
	    v_mul_f32_e32 v235, 0x4b800000, v231
	    v_cmp_gt_f32_e64 s[4:5], s54, v230
	    v_cmp_gt_f32_e32 vcc, s54, v231
	    s_nop 1
	    v_cndmask_b32_e64 v230, v230, v234, s[4:5]
	    v_cndmask_b32_e32 v231, v231, v235, vcc
	    v_rsq_f32_e32 v230, v230
	    v_rsq_f32_e32 v231, v231
	    s_nop 0
	    v_mul_f32_e32 v234, 0x45800000, v230
	    v_mul_f32_e32 v235, 0x45800000, v231
	    v_cndmask_b32_e64 v230, v230, v234, s[4:5]
	    v_cndmask_b32_e32 v231, v231, v235, vcc
	    v_mul_f32_e32 v228, v230, v228
	    v_mul_f32_e32 v229, v231, v229
	    v_mul_f32_e32 v228, v184, v228
	    v_mul_f32_e32 v229, v185, v229
	    v_bfe_u32 v234, v228, 16, 1
	    v_bfe_u32 v235, v229, 16, 1
	    v_add3_u32 v228, v228, v234, s55
	    v_add3_u32 v229, v229, v235, s55
	    v_perm_b32 v22, v229, v228, v194
	    global_store_dword v[202:203], v22, off
	v_mul_f32_e32 v242, 0x4b800000, v238
	    v_mul_f32_e32 v243, 0x4b800000, v239
	    v_cmp_gt_f32_e64 s[4:5], s54, v238
	    v_cmp_gt_f32_e32 vcc, s54, v239
	    s_nop 1
	    v_cndmask_b32_e64 v238, v238, v242, s[4:5]
	    v_cndmask_b32_e32 v239, v239, v243, vcc
	    v_rsq_f32_e32 v238, v238
	    v_rsq_f32_e32 v239, v239
	    s_nop 0
	    v_mul_f32_e32 v242, 0x45800000, v238
	    v_mul_f32_e32 v243, 0x45800000, v239
	    v_cndmask_b32_e64 v238, v238, v242, s[4:5]
	    v_cndmask_b32_e32 v239, v239, v243, vcc
	    v_mul_f32_e32 v236, v238, v236
	    v_mul_f32_e32 v237, v239, v237
	    v_mul_f32_e32 v236, v184, v236
	    v_mul_f32_e32 v237, v185, v237
	    v_bfe_u32 v242, v236, 16, 1
	    v_bfe_u32 v243, v237, 16, 1
	    v_add3_u32 v236, v236, v242, s55
	    v_add3_u32 v237, v237, v243, s55
	    v_perm_b32 v19, v237, v236, v194
	    global_store_dword v[200:201], v19, off offset:256
	v_mul_f32_e32 v250, 0x4b800000, v246
	    v_mul_f32_e32 v251, 0x4b800000, v247
	    v_cmp_gt_f32_e64 s[4:5], s54, v246
	    v_cmp_gt_f32_e32 vcc, s54, v247
	    s_nop 1
	    v_cndmask_b32_e64 v246, v246, v250, s[4:5]
	    v_cndmask_b32_e32 v247, v247, v251, vcc
	    v_rsq_f32_e32 v246, v246
	    v_rsq_f32_e32 v247, v247
	    s_nop 0
	    v_mul_f32_e32 v250, 0x45800000, v246
	    v_mul_f32_e32 v251, 0x45800000, v247
	    v_cndmask_b32_e64 v246, v246, v250, s[4:5]
	    v_cndmask_b32_e32 v247, v247, v251, vcc
	    v_mul_f32_e32 v244, v246, v244
	    v_mul_f32_e32 v245, v247, v245
	    v_mul_f32_e32 v244, v184, v244
	    v_mul_f32_e32 v245, v185, v245
	    v_bfe_u32 v250, v244, 16, 1
	    v_bfe_u32 v251, v245, 16, 1
	    v_add3_u32 v244, v244, v250, s55
	    v_add3_u32 v245, v245, v251, s55
	    v_perm_b32 v20, v245, v244, v194
	    global_store_dword v[202:203], v20, off offset:256
	s_cmpk_eq_i32 s63, 0x50
	s_cbranch_scc1 .Lkn5_s_1038_1_1
	s_waitcnt vmcnt(20)
	s_branch .Lkn5_e_1038_1_1

; __device__ __forceinline__ float bf2f(unsigned short u) { return __uint_as_float((unsigned)u << 16); }
; __device__ __forceinline__ void knorm_item(const KArgs& a, int l, int item, int wave, int lane) {
;     ...
;         for (int i = 0; i < 16; ++i) { const int task = item * 1024 + wave * 128 + r0 + i, row = task >> 2, which = (task >> 1) & 1, g = task & 1;
;             v[i] = bf2f(Z[(size_t)row * ZW + (which ? ZC_KW : ZC_KS) + g * 64 + lane]); }
; #pragma unroll
;         for (int i = 0; i < 16; ++i) { const int task = item * 1024 + wave * 128 + r0 + i, row = task >> 2, which = (task >> 1) & 1, g = task & 1;
;             const float rstd = rsqrtf(wave_sum(v[i] * v[i]) * (1.f / 64.f) + EPS);
.Lkn5_e_1038_1_1:
	v_lshlrev_b32_e32 v220, 16, v17
	v_and_b32_e32 v221, 0xffff0000, v17
	v_lshlrev_b32_e32 v228, 16, v18
	v_and_b32_e32 v229, 0xffff0000, v18
	v_lshlrev_b32_e32 v236, 16, v15
	v_and_b32_e32 v237, 0xffff0000, v15
	v_lshlrev_b32_e32 v244, 16, v16
	v_and_b32_e32 v245, 0xffff0000, v16
	v_mul_f32_e32 v224, v220, v220
	v_mul_f32_e32 v225, v221, v221
	v_mul_f32_e32 v232, v228, v228
	v_mul_f32_e32 v233, v229, v229
	v_mul_f32_e32 v240, v236, v236
	v_mul_f32_e32 v241, v237, v237
	v_mul_f32_e32 v248, v244, v244
	v_mul_f32_e32 v249, v245, v245
	v_fma_f32 v222, v220, v220, v225
	v_fma_f32 v223, v221, v221, v224
	v_fma_f32 v230, v228, v228, v233
	v_fma_f32 v231, v229, v229, v232
	v_fma_f32 v238, v236, v236, v241
	v_fma_f32 v239, v237, v237, v240
	v_fma_f32 v246, v244, v244, v249
	v_fma_f32 v247, v245, v245, v248
	v_add_f32_dpp v222, v222, v222 quad_perm:[1,0,3,2] row_mask:0xf bank_mask:0xf
	v_add_f32_dpp v223, v223, v223 quad_perm:[1,0,3,2] row_mask:0xf bank_mask:0xf
	v_add_f32_dpp v230, v230, v230 quad_perm:[1,0,3,2] row_mask:0xf bank_mask:0xf
	v_add_f32_dpp v231, v231, v231 quad_perm:[1,0,3,2] row_mask:0xf bank_mask:0xf
	v_add_f32_dpp v238, v238, v238 quad_perm:[1,0,3,2] row_mask:0xf bank_mask:0xf
	v_add_f32_dpp v239, v239, v239 quad_perm:[1,0,3,2] row_mask:0xf bank_mask:0xf
	v_add_f32_dpp v246, v246, v246 quad_perm:[1,0,3,2] row_mask:0xf bank_mask:0xf
	v_add_f32_dpp v247, v247, v247 quad_perm:[1,0,3,2] row_mask:0xf bank_mask:0xf
	v_add_f32_dpp v222, v222, v222 quad_perm:[2,3,0,1] row_mask:0xf bank_mask:0xf
	v_add_f32_dpp v223, v223, v223 quad_perm:[2,3,0,1] row_mask:0xf bank_mask:0xf
	v_add_f32_dpp v230, v230, v230 quad_perm:[2,3,0,1] row_mask:0xf bank_mask:0xf
	v_add_f32_dpp v231, v231, v231 quad_perm:[2,3,0,1] row_mask:0xf bank_mask:0xf
	v_add_f32_dpp v238, v238, v238 quad_perm:[2,3,0,1] row_mask:0xf bank_mask:0xf
	v_add_f32_dpp v239, v239, v239 quad_perm:[2,3,0,1] row_mask:0xf bank_mask:0xf
	v_add_f32_dpp v246, v246, v246 quad_perm:[2,3,0,1] row_mask:0xf bank_mask:0xf
	v_add_f32_dpp v247, v247, v247 quad_perm:[2,3,0,1] row_mask:0xf bank_mask:0xf
	ds_bpermute_b32 v224, v11, v222
	ds_bpermute_b32 v225, v11, v223
	ds_bpermute_b32 v232, v11, v230
	ds_bpermute_b32 v233, v11, v231
	ds_bpermute_b32 v240, v11, v238
	ds_bpermute_b32 v241, v11, v239
	ds_bpermute_b32 v248, v11, v246
	ds_bpermute_b32 v249, v11, v247
	s_waitcnt lgkmcnt(0)
	v_add_f32_e32 v222, v222, v224
	v_add_f32_e32 v223, v223, v225
	v_add_f32_e32 v230, v230, v232
	v_add_f32_e32 v231, v231, v233
	v_add_f32_e32 v238, v238, v240
	v_add_f32_e32 v239, v239, v241
	v_add_f32_e32 v246, v246, v248
	v_add_f32_e32 v247, v247, v249
	v_add_f32_dpp v222, v222, v222 row_ror:8 row_mask:0xf bank_mask:0xf
	v_add_f32_dpp v223, v223, v223 row_ror:8 row_mask:0xf bank_mask:0xf
	v_add_f32_dpp v230, v230, v230 row_ror:8 row_mask:0xf bank_mask:0xf
	v_add_f32_dpp v231, v231, v231 row_ror:8 row_mask:0xf bank_mask:0xf
	v_add_f32_dpp v238, v238, v238 row_ror:8 row_mask:0xf bank_mask:0xf
	v_add_f32_dpp v239, v239, v239 row_ror:8 row_mask:0xf bank_mask:0xf
	v_add_f32_dpp v246, v246, v246 row_ror:8 row_mask:0xf bank_mask:0xf
	v_add_f32_dpp v247, v247, v247 row_ror:8 row_mask:0xf bank_mask:0xf
	ds_bpermute_b32 v224, v13, v222
	ds_bpermute_b32 v225, v13, v223
	ds_bpermute_b32 v232, v13, v230
	ds_bpermute_b32 v233, v13, v231
	ds_bpermute_b32 v240, v13, v238
	ds_bpermute_b32 v241, v13, v239
	ds_bpermute_b32 v248, v13, v246
	ds_bpermute_b32 v249, v13, v247
	s_waitcnt lgkmcnt(0)
; __device__ __forceinline__ unsigned f2bf(float f) { unsigned u = __float_as_uint(f); return (u + 0x7fffu + ((u >> 16) & 1u)) >> 16; }
; __device__ __forceinline__ void knorm_item(const KArgs& a, int l, int item, int wave, int lane) {
;     ...
;         for (int i = 0; i < 16; ++i) { const int task = item * 1024 + wave * 128 + r0 + i, row = task >> 2, which = (task >> 1) & 1, g = task & 1;
;             const float rstd = rsqrtf(wave_sum(v[i] * v[i]) * (1.f / 64.f) + EPS);
;             bf16_t* dst = (bf16_t*)(a.ws + (which ? WS_KWN : WS_KSN));
;             dst[(size_t)row * 128 + g * 64 + lane] = (bf16_t)f2bf(v[i] * rstd * kg); }
	v_add_f32_e32 v222, v222, v224
	v_add_f32_e32 v223, v223, v225
	v_add_f32_e32 v230, v230, v232
	v_add_f32_e32 v231, v231, v233
	v_add_f32_e32 v238, v238, v240
	v_add_f32_e32 v239, v239, v241
	v_add_f32_e32 v246, v246, v248
	v_add_f32_e32 v247, v247, v249
	v_fma_f32 v222, v222, s28, v195
	v_fma_f32 v223, v223, s28, v195
	v_fma_f32 v230, v230, s28, v195
	v_fma_f32 v231, v231, s28, v195
	v_fma_f32 v238, v238, s28, v195
	v_fma_f32 v239, v239, s28, v195
	v_fma_f32 v246, v246, s28, v195
	v_fma_f32 v247, v247, s28, v195
	v_mul_f32_e32 v226, 0x4b800000, v222
	    v_mul_f32_e32 v227, 0x4b800000, v223
	    v_cmp_gt_f32_e64 s[4:5], s54, v222
	    v_cmp_gt_f32_e32 vcc, s54, v223
	    s_nop 1
	    v_cndmask_b32_e64 v222, v222, v226, s[4:5]
	    v_cndmask_b32_e32 v223, v223, v227, vcc
	    v_rsq_f32_e32 v222, v222
	    v_rsq_f32_e32 v223, v223
	    s_nop 0
	    v_mul_f32_e32 v226, 0x45800000, v222
	    v_mul_f32_e32 v227, 0x45800000, v223
	    v_cndmask_b32_e64 v222, v222, v226, s[4:5]
	    v_cndmask_b32_e32 v223, v223, v227, vcc
	    v_mul_f32_e32 v220, v222, v220
	    v_mul_f32_e32 v221, v223, v221
	    v_mul_f32_e32 v220, v184, v220
	    v_mul_f32_e32 v221, v185, v221
	    v_bfe_u32 v226, v220, 16, 1
	    v_bfe_u32 v227, v221, 16, 1
	    v_add3_u32 v220, v220, v226, s55
	    v_add3_u32 v221, v221, v227, s55
	    v_perm_b32 v17, v221, v220, v194
	    global_store_dword v[200:201], v17, off offset:512
	v_mul_f32_e32 v234, 0x4b800000, v230
	    v_mul_f32_e32 v235, 0x4b800000, v231
	    v_cmp_gt_f32_e64 s[4:5], s54, v230
	    v_cmp_gt_f32_e32 vcc, s54, v231
	    s_nop 1
	    v_cndmask_b32_e64 v230, v230, v234, s[4:5]
	    v_cndmask_b32_e32 v231, v231, v235, vcc
	    v_rsq_f32_e32 v230, v230
	    v_rsq_f32_e32 v231, v231
	    s_nop 0
	    v_mul_f32_e32 v234, 0x45800000, v230
	    v_mul_f32_e32 v235, 0x45800000, v231
	    v_cndmask_b32_e64 v230, v230, v234, s[4:5]
	    v_cndmask_b32_e32 v231, v231, v235, vcc
	    v_mul_f32_e32 v228, v230, v228
	    v_mul_f32_e32 v229, v231, v229
	    v_mul_f32_e32 v228, v184, v228
	    v_mul_f32_e32 v229, v185, v229
	    v_bfe_u32 v234, v228, 16, 1
	    v_bfe_u32 v235, v229, 16, 1
	    v_add3_u32 v228, v228, v234, s55
	    v_add3_u32 v229, v229, v235, s55
	    v_perm_b32 v18, v229, v228, v194
	    global_store_dword v[202:203], v18, off offset:512
	v_mul_f32_e32 v242, 0x4b800000, v238
	    v_mul_f32_e32 v243, 0x4b800000, v239
	    v_cmp_gt_f32_e64 s[4:5], s54, v238
	    v_cmp_gt_f32_e32 vcc, s54, v239
	    s_nop 1
	    v_cndmask_b32_e64 v238, v238, v242, s[4:5]
	    v_cndmask_b32_e32 v239, v239, v243, vcc
	    v_rsq_f32_e32 v238, v238
	    v_rsq_f32_e32 v239, v239
	    s_nop 0
	    v_mul_f32_e32 v242, 0x45800000, v238
	    v_mul_f32_e32 v243, 0x45800000, v239
	    v_cndmask_b32_e64 v238, v238, v242, s[4:5]
	    v_cndmask_b32_e32 v239, v239, v243, vcc
	    v_mul_f32_e32 v236, v238, v236
	    v_mul_f32_e32 v237, v239, v237
	    v_mul_f32_e32 v236, v184, v236
	    v_mul_f32_e32 v237, v185, v237
	    v_bfe_u32 v242, v236, 16, 1
	    v_bfe_u32 v243, v237, 16, 1
	    v_add3_u32 v236, v236, v242, s55
	    v_add3_u32 v237, v237, v243, s55
	    v_perm_b32 v15, v237, v236, v194
	    global_store_dword v[200:201], v15, off offset:768
	v_mul_f32_e32 v250, 0x4b800000, v246
	    v_mul_f32_e32 v251, 0x4b800000, v247
	    v_cmp_gt_f32_e64 s[4:5], s54, v246
	    v_cmp_gt_f32_e32 vcc, s54, v247
	    s_nop 1
	    v_cndmask_b32_e64 v246, v246, v250, s[4:5]
	    v_cndmask_b32_e32 v247, v247, v251, vcc
	    v_rsq_f32_e32 v246, v246
	    v_rsq_f32_e32 v247, v247
	    s_nop 0
	    v_mul_f32_e32 v250, 0x45800000, v246
	    v_mul_f32_e32 v251, 0x45800000, v247
	    v_cndmask_b32_e64 v246, v246, v250, s[4:5]
	    v_cndmask_b32_e32 v247, v247, v251, vcc
	    v_mul_f32_e32 v244, v246, v244
	    v_mul_f32_e32 v245, v247, v245
	    v_mul_f32_e32 v244, v184, v244
	    v_mul_f32_e32 v245, v185, v245
	    v_bfe_u32 v250, v244, 16, 1
	    v_bfe_u32 v251, v245, 16, 1
	    v_add3_u32 v244, v244, v250, s55
	    v_add3_u32 v245, v245, v251, s55
	    v_perm_b32 v16, v245, v244, v194
	    global_store_dword v[202:203], v16, off offset:768
	s_add_i32 s63, s63, 32
	s_cmpk_gt_u32 s63, 0x6f
	s_cbranch_scc0 .LBB0_1038
	s_mov_b64 s[0:1], 0
